# v29 = v27 with MT4 k-loop loads of the first six staging registers re-issued right behind their LDS write (tile t+2), rest in ks0
# speedup vs baseline: 1.0067x; 1.0067x over previous
.LBB0_301:
	s_mul_hi_u32 s0, s55, s25
	s_mul_i32 s1, s0, s20
	s_sub_i32 s1, s55, s1
	s_add_i32 s8, s0, 1
	s_sub_i32 s12, s1, s20
	s_cmp_ge_u32 s1, s20
	s_cselect_b32 s0, s8, s0
	s_cselect_b32 s1, s12, s1
	s_add_i32 s8, s0, 1
	s_cmp_ge_u32 s1, s20
	s_cselect_b32 s0, s8, s0
	s_add_i32 s1, s0, s23
	s_mul_i32 s0, s0, s20
	s_sub_i32 s0, s55, s0
	s_add_i32 s0, s0, s19
	s_lshl_b32 s12, s1, 8
	s_lshl_b32 s8, s0, 7
	s_mov_b64 s[0:1], s[30:31]
	v_mov_b32_e32 v0, v177
	s_mov_b32 s13, s9
	v_mbcnt_lo_u32_b32 v0, -1, v0
	v_mbcnt_hi_u32_b32 v0, -1, v0
	v_add_u32_e32 v182, s33, v0
	s_lshl_b64 s[16:17], s[12:13], 11
	v_ashrrev_i32_e32 v0, 3, v182
	v_lshlrev_b32_e32 v1, 3, v182
	s_add_u32 s56, s14, s16
	v_and_b32_e32 v6, 56, v1
	v_lshlrev_b32_e32 v1, 11, v0
	s_addc_u32 s57, s15, s17
	v_lshl_or_b32 v176, v6, 1, v1
	v_mul_lo_u32 v7, v0, s21
	v_lshl_add_u64 v[0:1], s[56:57], 0, v[176:177]
	v_add_co_u32_e32 v2, vcc, s26, v0
	s_lshl_b64 s[58:59], s[8:9], 11
	s_nop 0
	v_addc_co_u32_e32 v3, vcc, 0, v1, vcc
	v_add_co_u32_e32 v4, vcc, s27, v0
	s_add_u32 s58, s30, s58
	s_nop 0
	v_addc_co_u32_e32 v5, vcc, 0, v1, vcc
	global_load_dwordx4 v[128:131], v[2:3], off
	global_load_dwordx4 v[132:135], v[4:5], off
	v_add_co_u32_e32 v2, vcc, s34, v0
	s_addc_u32 s59, s31, s59
	s_nop 0
	v_addc_co_u32_e32 v3, vcc, 0, v1, vcc
	v_add_co_u32_e32 v4, vcc, s35, v0
	v_lshl_add_u64 v[178:179], s[58:59], 0, v[176:177]
	s_nop 0
	v_addc_co_u32_e32 v5, vcc, 0, v1, vcc
	global_load_dwordx4 v[136:139], v[2:3], off
	global_load_dwordx4 v[144:147], v[4:5], off
	v_add_co_u32_e32 v2, vcc, s36, v0
	v_bfe_u32 v185, v182, 6, 1
	s_nop 0
	v_addc_co_u32_e32 v3, vcc, 0, v1, vcc
	v_add_co_u32_e32 v4, vcc, s37, v0
	v_and_b32_e32 v184, 31, v182
	s_nop 0
	v_addc_co_u32_e32 v5, vcc, 0, v1, vcc
	v_add_co_u32_e32 v0, vcc, s38, v0
	global_load_dwordx4 v[148:151], v[2:3], off
	global_load_dwordx4 v[152:155], v[4:5], off
	v_addc_co_u32_e32 v1, vcc, 0, v1, vcc
	v_add_co_u32_e32 v2, vcc, s26, v178
	global_load_dwordx4 v[164:167], v176, s[56:57]
	global_load_dwordx4 v[140:143], v176, s[58:59]
	v_addc_co_u32_e32 v3, vcc, 0, v179, vcc
	global_load_dwordx4 v[156:159], v[0:1], off
	global_load_dwordx4 v[160:163], v[2:3], off
	v_add_co_u32_e32 v0, vcc, s27, v178
	v_bfe_u32 v186, v182, 5, 1
	s_nop 0
	v_addc_co_u32_e32 v1, vcc, 0, v179, vcc
	v_add_co_u32_e32 v2, vcc, s34, v178
	s_add_u32 s16, s30, s16
	s_nop 0
	v_addc_co_u32_e32 v3, vcc, 0, v179, vcc
	global_load_dwordx4 v[168:171], v[0:1], off
	global_load_dwordx4 v[172:175], v[2:3], off
	v_and_b32_e32 v0, 0xfffff9f, v182
	v_lshl_or_b32 v2, v185, 6, v184
	v_mul_lo_u32 v3, v0, s39
	v_or_b32_e32 v0, 0x60, v182
	v_lshlrev_b32_e32 v1, 4, v186
	v_mul_lo_u32 v4, v0, s39
	v_mul_u32_u24_e32 v2, 0x90, v2
	s_addc_u32 s17, s31, s17
	v_mov_b32_e32 v0, 0
	v_add_lshl_u32 v189, v7, v6, 1
	v_lshl_add_u64 v[180:181], s[16:17], 0, v[176:177]
	s_mov_b64 s[16:17], 0
	v_add_u32_e32 v188, v1, v3
	v_add_u32_e32 v187, v1, v4
	v_add_u32_e32 v176, v1, v2
	v_mov_b32_e32 v1, v0
	v_mov_b32_e32 v2, v0
	v_mov_b32_e32 v3, v0
	v_mov_b32_e32 v4, v0
	v_mov_b32_e32 v5, v0
	v_mov_b32_e32 v6, v0
	v_mov_b32_e32 v7, v0
	v_mov_b32_e32 v8, v0
	v_mov_b32_e32 v9, v0
	v_mov_b32_e32 v10, v0
	v_mov_b32_e32 v11, v0
	v_mov_b32_e32 v12, v0
	v_mov_b32_e32 v13, v0
	v_mov_b32_e32 v14, v0
	v_mov_b32_e32 v15, v0
	v_mov_b32_e32 v16, v0
	v_mov_b32_e32 v17, v0
	v_mov_b32_e32 v18, v0
	v_mov_b32_e32 v19, v0
	v_mov_b32_e32 v20, v0
	v_mov_b32_e32 v21, v0
	v_mov_b32_e32 v22, v0
	v_mov_b32_e32 v23, v0
	v_mov_b32_e32 v24, v0
	v_mov_b32_e32 v25, v0
	v_mov_b32_e32 v26, v0
	v_mov_b32_e32 v27, v0
	v_mov_b32_e32 v28, v0
	v_mov_b32_e32 v29, v0
	v_mov_b32_e32 v30, v0
	v_mov_b32_e32 v31, v0
	v_mov_b32_e32 v32, v0
	v_mov_b32_e32 v33, v0
	v_mov_b32_e32 v34, v0
	v_mov_b32_e32 v35, v0
	v_mov_b32_e32 v36, v0
	v_mov_b32_e32 v37, v0
	v_mov_b32_e32 v38, v0
	v_mov_b32_e32 v39, v0
	v_mov_b32_e32 v40, v0
	v_mov_b32_e32 v41, v0
	v_mov_b32_e32 v42, v0
	v_mov_b32_e32 v43, v0
	v_mov_b32_e32 v44, v0
	v_mov_b32_e32 v45, v0
	v_mov_b32_e32 v46, v0
	v_mov_b32_e32 v47, v0
	v_mov_b32_e32 v48, v0
	v_mov_b32_e32 v49, v0
	v_mov_b32_e32 v50, v0
	v_mov_b32_e32 v51, v0
	v_mov_b32_e32 v52, v0
	v_mov_b32_e32 v53, v0
	v_mov_b32_e32 v54, v0
	v_mov_b32_e32 v55, v0
	v_mov_b32_e32 v56, v0
	v_mov_b32_e32 v57, v0
	v_mov_b32_e32 v58, v0
	v_mov_b32_e32 v59, v0
	v_mov_b32_e32 v60, v0
	v_mov_b32_e32 v61, v0
	v_mov_b32_e32 v62, v0
	v_mov_b32_e32 v63, v0
	v_mov_b32_e32 v64, v0
	v_mov_b32_e32 v65, v0
	v_mov_b32_e32 v66, v0
	v_mov_b32_e32 v67, v0
	v_mov_b32_e32 v68, v0
	v_mov_b32_e32 v69, v0
	v_mov_b32_e32 v70, v0
	v_mov_b32_e32 v71, v0
	v_mov_b32_e32 v72, v0
	v_mov_b32_e32 v73, v0
	v_mov_b32_e32 v74, v0
	v_mov_b32_e32 v75, v0
	v_mov_b32_e32 v76, v0
	v_mov_b32_e32 v77, v0
	v_mov_b32_e32 v78, v0
	v_mov_b32_e32 v79, v0
	v_mov_b32_e32 v80, v0
	v_mov_b32_e32 v81, v0
	v_mov_b32_e32 v82, v0
	v_mov_b32_e32 v83, v0
	v_mov_b32_e32 v84, v0
	v_mov_b32_e32 v85, v0
	v_mov_b32_e32 v86, v0
	v_mov_b32_e32 v87, v0
	v_mov_b32_e32 v88, v0
	v_mov_b32_e32 v89, v0
	v_mov_b32_e32 v90, v0
	v_mov_b32_e32 v91, v0
	v_mov_b32_e32 v92, v0
	v_mov_b32_e32 v93, v0
	v_mov_b32_e32 v94, v0
	v_mov_b32_e32 v95, v0
	v_mov_b32_e32 v96, v0
	v_mov_b32_e32 v97, v0
	v_mov_b32_e32 v98, v0
	v_mov_b32_e32 v99, v0
	v_mov_b32_e32 v100, v0
	v_mov_b32_e32 v101, v0
	v_mov_b32_e32 v102, v0
	v_mov_b32_e32 v103, v0
	v_mov_b32_e32 v104, v0
	v_mov_b32_e32 v105, v0
	v_mov_b32_e32 v106, v0
	v_mov_b32_e32 v107, v0
	v_mov_b32_e32 v108, v0
	v_mov_b32_e32 v109, v0
	v_mov_b32_e32 v110, v0
	v_mov_b32_e32 v111, v0
	v_mov_b32_e32 v112, v0
	v_mov_b32_e32 v113, v0
	v_mov_b32_e32 v114, v0
	v_mov_b32_e32 v115, v0
	v_mov_b32_e32 v116, v0
	v_mov_b32_e32 v117, v0
	v_mov_b32_e32 v118, v0
	v_mov_b32_e32 v119, v0
	v_mov_b32_e32 v120, v0
	v_mov_b32_e32 v121, v0
	v_mov_b32_e32 v122, v0
	v_mov_b32_e32 v123, v0
	v_mov_b32_e32 v124, v0
	v_mov_b32_e32 v125, v0
	v_mov_b32_e32 v126, v0
	v_mov_b32_e32 v127, v0
	v_readfirstlane_b32 s40, v180
	v_readfirstlane_b32 s41, v181
	v_readfirstlane_b32 s42, v178
	v_readfirstlane_b32 s43, v179
	v_lshrrev_b32_e32 v198, 3, v182
	v_and_b32_e32 v199, 7, v182
	v_lshlrev_b32_e32 v198, 11, v198
	v_lshl_or_b32 v190, v199, 4, v198
	s_lshl_b32 s44, s33, 8
	s_sub_u32 s40, s40, s44
	s_subb_u32 s41, s41, 0
	s_sub_u32 s42, s42, s44
	s_subb_u32 s43, s43, 0
	s_add_u32 s40, s40, 0x2957980
	s_addc_u32 s41, s41, 0
	s_add_u32 s42, s42, 0x80
	s_addc_u32 s43, s43, 0
	v_add_u32_e32 v191, 0x10000, v190
	v_add_u32_e32 v192, 0x20000, v190
	v_add_u32_e32 v193, 0x30000, v190
	v_add_u32_e32 v194, 0x40000, v190
	v_add_u32_e32 v195, 0x50000, v190
	v_add_u32_e32 v196, 0x60000, v190
	v_add_u32_e32 v197, 0x70000, v190
	s_waitcnt lgkmcnt(0)
	s_barrier
	s_waitcnt vmcnt(0)
	ds_write_b128 v189, v[164:167]
	ds_write_b128 v189, v[128:131] offset:4608
	ds_write_b128 v189, v[132:135] offset:9216
	ds_write_b128 v189, v[136:139] offset:13824
	ds_write_b128 v189, v[144:147] offset:18432
	ds_write_b128 v189, v[148:151] offset:23040
	ds_write_b128 v189, v[152:155] offset:27648
	ds_write_b128 v189, v[156:159] offset:32256
	ds_write_b128 v189, v[140:143] offset:36864
	ds_write_b128 v189, v[160:163] offset:41472
	ds_write_b128 v189, v[168:171] offset:46080
	ds_write_b128 v189, v[172:175] offset:50688
	global_load_dwordx4 v[164:167], v190, s[40:41]
	global_load_dwordx4 v[128:131], v191, s[40:41]
	global_load_dwordx4 v[132:135], v192, s[40:41]
	global_load_dwordx4 v[136:139], v193, s[40:41]
	global_load_dwordx4 v[144:147], v194, s[40:41]
	global_load_dwordx4 v[148:151], v195, s[40:41]
	s_waitcnt lgkmcnt(0)
	s_barrier
.LBB0_302:
	ds_read_b128 v[216:219], v176 offset:36864
	ds_read_b128 v[200:203], v188
	ds_read_b128 v[220:223], v176 offset:41472
	ds_read_b128 v[204:207], v188 offset:4608
	ds_read_b128 v[208:211], v188 offset:9216
	ds_read_b128 v[212:215], v187
	s_waitcnt lgkmcnt(4)
	v_mfma_f32_32x32x16_bf16 v[112:127], v[200:203], v[216:219], v[112:127]
	ds_read_b128 v[240:243], v176 offset:36896
	global_load_dwordx4 v[140:143], v190, s[42:43]
	s_waitcnt lgkmcnt(4)
	v_mfma_f32_32x32x16_bf16 v[96:111], v[200:203], v[220:223], v[96:111]
	ds_read_b128 v[224:227], v188 offset:32
	global_load_dwordx4 v[160:163], v191, s[42:43]
	s_waitcnt lgkmcnt(4)
	v_mfma_f32_32x32x16_bf16 v[80:95], v[204:207], v[216:219], v[80:95]
	ds_read_b128 v[244:247], v176 offset:41504
	global_load_dwordx4 v[168:171], v192, s[42:43]
	s_waitcnt lgkmcnt(5)
	v_mfma_f32_32x32x16_bf16 v[64:79], v[204:207], v[220:223], v[64:79]
	ds_read_b128 v[228:231], v188 offset:4640
	global_load_dwordx4 v[172:175], v193, s[42:43]
	s_waitcnt lgkmcnt(5)
	v_mfma_f32_32x32x16_bf16 v[48:63], v[208:211], v[216:219], v[48:63]
	ds_read_b128 v[232:235], v188 offset:9248
	global_load_dwordx4 v[152:155], v196, s[40:41]
	s_waitcnt lgkmcnt(6)
	v_mfma_f32_32x32x16_bf16 v[32:47], v[208:211], v[220:223], v[32:47]
	ds_read_b128 v[236:239], v187 offset:32
	global_load_dwordx4 v[156:159], v197, s[40:41]
	s_add_u32 s40, s40, 0x80
	s_addc_u32 s41, s41, 0
	s_add_u32 s42, s42, 0x80
	s_addc_u32 s43, s43, 0
	s_add_u32 s16, s16, 0x80
	s_waitcnt lgkmcnt(6)
	v_mfma_f32_32x32x16_bf16 v[16:31], v[212:215], v[216:219], v[16:31]
	s_waitcnt lgkmcnt(6)
	v_mfma_f32_32x32x16_bf16 v[0:15], v[212:215], v[220:223], v[0:15]
	s_waitcnt lgkmcnt(4)
	v_mfma_f32_32x32x16_bf16 v[112:127], v[224:227], v[240:243], v[112:127]
	ds_read_b128 v[200:203], v188 offset:64
	s_waitcnt lgkmcnt(4)
	v_mfma_f32_32x32x16_bf16 v[96:111], v[224:227], v[244:247], v[96:111]
	ds_read_b128 v[204:207], v188 offset:4672
	s_waitcnt lgkmcnt(4)
	v_mfma_f32_32x32x16_bf16 v[80:95], v[228:231], v[240:243], v[80:95]
	ds_read_b128 v[208:211], v188 offset:9280
	s_waitcnt lgkmcnt(5)
	v_mfma_f32_32x32x16_bf16 v[64:79], v[228:231], v[244:247], v[64:79]
	ds_read_b128 v[212:215], v187 offset:64
	s_waitcnt lgkmcnt(5)
	v_mfma_f32_32x32x16_bf16 v[48:63], v[232:235], v[240:243], v[48:63]
	ds_read_b128 v[216:219], v176 offset:36928
	s_waitcnt lgkmcnt(6)
	v_mfma_f32_32x32x16_bf16 v[32:47], v[232:235], v[244:247], v[32:47]
	ds_read_b128 v[220:223], v176 offset:41536
	s_waitcnt lgkmcnt(6)
	v_mfma_f32_32x32x16_bf16 v[16:31], v[236:239], v[240:243], v[16:31]
	s_waitcnt lgkmcnt(6)
	v_mfma_f32_32x32x16_bf16 v[0:15], v[236:239], v[244:247], v[0:15]
	s_waitcnt lgkmcnt(1)
	v_mfma_f32_32x32x16_bf16 v[112:127], v[200:203], v[216:219], v[112:127]
	ds_read_b128 v[224:227], v188 offset:96
	s_waitcnt lgkmcnt(1)
	v_mfma_f32_32x32x16_bf16 v[96:111], v[200:203], v[220:223], v[96:111]
	ds_read_b128 v[228:231], v188 offset:4704
	s_waitcnt lgkmcnt(3)
	v_mfma_f32_32x32x16_bf16 v[80:95], v[204:207], v[216:219], v[80:95]
	ds_read_b128 v[232:235], v188 offset:9312
	s_waitcnt lgkmcnt(3)
	v_mfma_f32_32x32x16_bf16 v[64:79], v[204:207], v[220:223], v[64:79]
	ds_read_b128 v[236:239], v187 offset:96
	s_waitcnt lgkmcnt(5)
	v_mfma_f32_32x32x16_bf16 v[48:63], v[208:211], v[216:219], v[48:63]
	ds_read_b128 v[240:243], v176 offset:36960
	s_waitcnt lgkmcnt(5)
	v_mfma_f32_32x32x16_bf16 v[32:47], v[208:211], v[220:223], v[32:47]
	ds_read_b128 v[244:247], v176 offset:41568
	s_waitcnt lgkmcnt(7)
	v_mfma_f32_32x32x16_bf16 v[16:31], v[212:215], v[216:219], v[16:31]
	s_waitcnt lgkmcnt(6)
	v_mfma_f32_32x32x16_bf16 v[0:15], v[212:215], v[220:223], v[0:15]
	s_waitcnt lgkmcnt(0)
	s_barrier
	s_waitcnt vmcnt(0)
	s_waitcnt lgkmcnt(1)
	v_mfma_f32_32x32x16_bf16 v[112:127], v[224:227], v[240:243], v[112:127]
	ds_write_b128 v189, v[164:167]
	ds_write_b128 v189, v[128:131] offset:4608
	s_waitcnt lgkmcnt(2)
	v_mfma_f32_32x32x16_bf16 v[96:111], v[224:227], v[244:247], v[96:111]
	ds_write_b128 v189, v[132:135] offset:9216
	global_load_dwordx4 v[164:167], v190, s[40:41]
	s_waitcnt lgkmcnt(4)
	v_mfma_f32_32x32x16_bf16 v[80:95], v[228:231], v[240:243], v[80:95]
	ds_write_b128 v189, v[136:139] offset:13824
	ds_write_b128 v189, v[144:147] offset:18432
	global_load_dwordx4 v[128:131], v191, s[40:41]
	s_waitcnt lgkmcnt(5)
	v_mfma_f32_32x32x16_bf16 v[64:79], v[228:231], v[244:247], v[64:79]
	ds_write_b128 v189, v[148:151] offset:23040
	global_load_dwordx4 v[132:135], v192, s[40:41]
	s_waitcnt lgkmcnt(7)
	v_mfma_f32_32x32x16_bf16 v[48:63], v[232:235], v[240:243], v[48:63]
	ds_write_b128 v189, v[152:155] offset:27648
	ds_write_b128 v189, v[156:159] offset:32256
	global_load_dwordx4 v[136:139], v193, s[40:41]
	s_waitcnt lgkmcnt(8)
	v_mfma_f32_32x32x16_bf16 v[32:47], v[232:235], v[244:247], v[32:47]
	ds_write_b128 v189, v[140:143] offset:36864
	global_load_dwordx4 v[144:147], v194, s[40:41]
	s_waitcnt lgkmcnt(10)
	v_mfma_f32_32x32x16_bf16 v[16:31], v[236:239], v[240:243], v[16:31]
	ds_write_b128 v189, v[160:163] offset:41472
	ds_write_b128 v189, v[168:171] offset:46080
	global_load_dwordx4 v[148:151], v195, s[40:41]
	s_waitcnt lgkmcnt(11)
	v_mfma_f32_32x32x16_bf16 v[0:15], v[236:239], v[244:247], v[0:15]
	ds_write_b128 v189, v[172:175] offset:50688
	s_waitcnt lgkmcnt(0)
	s_barrier
	s_cmpk_lg_i32 s16, 0x780
	s_cbranch_scc1 .LBB0_302
	ds_read_b128 v[216:219], v176 offset:36864
	ds_read_b128 v[200:203], v188
	ds_read_b128 v[220:223], v176 offset:41472
	ds_read_b128 v[204:207], v188 offset:4608
	ds_read_b128 v[208:211], v188 offset:9216
	ds_read_b128 v[212:215], v187
	s_waitcnt lgkmcnt(4)
	v_mfma_f32_32x32x16_bf16 v[112:127], v[200:203], v[216:219], v[112:127]
	ds_read_b128 v[240:243], v176 offset:36896
	s_waitcnt lgkmcnt(4)
	v_mfma_f32_32x32x16_bf16 v[96:111], v[200:203], v[220:223], v[96:111]
	ds_read_b128 v[224:227], v188 offset:32
	s_waitcnt lgkmcnt(4)
	v_mfma_f32_32x32x16_bf16 v[80:95], v[204:207], v[216:219], v[80:95]
	ds_read_b128 v[244:247], v176 offset:41504
	s_waitcnt lgkmcnt(5)
	v_mfma_f32_32x32x16_bf16 v[64:79], v[204:207], v[220:223], v[64:79]
	ds_read_b128 v[228:231], v188 offset:4640
	s_waitcnt lgkmcnt(5)
	v_mfma_f32_32x32x16_bf16 v[48:63], v[208:211], v[216:219], v[48:63]
	ds_read_b128 v[232:235], v188 offset:9248
	s_waitcnt lgkmcnt(6)
	v_mfma_f32_32x32x16_bf16 v[32:47], v[208:211], v[220:223], v[32:47]
	ds_read_b128 v[236:239], v187 offset:32
	s_waitcnt lgkmcnt(6)
	v_mfma_f32_32x32x16_bf16 v[16:31], v[212:215], v[216:219], v[16:31]
	s_waitcnt lgkmcnt(6)
	v_mfma_f32_32x32x16_bf16 v[0:15], v[212:215], v[220:223], v[0:15]
	s_waitcnt lgkmcnt(4)
	v_mfma_f32_32x32x16_bf16 v[112:127], v[224:227], v[240:243], v[112:127]
	ds_read_b128 v[200:203], v188 offset:64
	s_waitcnt lgkmcnt(4)
	v_mfma_f32_32x32x16_bf16 v[96:111], v[224:227], v[244:247], v[96:111]
	ds_read_b128 v[204:207], v188 offset:4672
	s_waitcnt lgkmcnt(4)
	v_mfma_f32_32x32x16_bf16 v[80:95], v[228:231], v[240:243], v[80:95]
	ds_read_b128 v[208:211], v188 offset:9280
	s_waitcnt lgkmcnt(5)
	v_mfma_f32_32x32x16_bf16 v[64:79], v[228:231], v[244:247], v[64:79]
	ds_read_b128 v[212:215], v187 offset:64
	s_waitcnt lgkmcnt(5)
	v_mfma_f32_32x32x16_bf16 v[48:63], v[232:235], v[240:243], v[48:63]
	ds_read_b128 v[216:219], v176 offset:36928
	s_waitcnt lgkmcnt(6)
	v_mfma_f32_32x32x16_bf16 v[32:47], v[232:235], v[244:247], v[32:47]
	ds_read_b128 v[220:223], v176 offset:41536
	s_waitcnt lgkmcnt(6)
	v_mfma_f32_32x32x16_bf16 v[16:31], v[236:239], v[240:243], v[16:31]
	s_waitcnt lgkmcnt(6)
	v_mfma_f32_32x32x16_bf16 v[0:15], v[236:239], v[244:247], v[0:15]
	s_waitcnt lgkmcnt(1)
	v_mfma_f32_32x32x16_bf16 v[112:127], v[200:203], v[216:219], v[112:127]
	ds_read_b128 v[224:227], v188 offset:96
	s_waitcnt lgkmcnt(1)
	v_mfma_f32_32x32x16_bf16 v[96:111], v[200:203], v[220:223], v[96:111]
	ds_read_b128 v[228:231], v188 offset:4704
	s_waitcnt lgkmcnt(3)
	v_mfma_f32_32x32x16_bf16 v[80:95], v[204:207], v[216:219], v[80:95]
	ds_read_b128 v[232:235], v188 offset:9312
	s_waitcnt lgkmcnt(3)
	v_mfma_f32_32x32x16_bf16 v[64:79], v[204:207], v[220:223], v[64:79]
	ds_read_b128 v[236:239], v187 offset:96
	s_waitcnt lgkmcnt(5)
	v_mfma_f32_32x32x16_bf16 v[48:63], v[208:211], v[216:219], v[48:63]
	ds_read_b128 v[240:243], v176 offset:36960
	s_waitcnt lgkmcnt(5)
	v_mfma_f32_32x32x16_bf16 v[32:47], v[208:211], v[220:223], v[32:47]
	ds_read_b128 v[244:247], v176 offset:41568
	s_waitcnt lgkmcnt(7)
	v_mfma_f32_32x32x16_bf16 v[16:31], v[212:215], v[216:219], v[16:31]
	s_waitcnt lgkmcnt(6)
	v_mfma_f32_32x32x16_bf16 v[0:15], v[212:215], v[220:223], v[0:15]
	s_waitcnt lgkmcnt(1)
	v_mfma_f32_32x32x16_bf16 v[112:127], v[224:227], v[240:243], v[112:127]
	s_waitcnt lgkmcnt(0)
	v_mfma_f32_32x32x16_bf16 v[96:111], v[224:227], v[244:247], v[96:111]
	s_waitcnt lgkmcnt(1)
	v_mfma_f32_32x32x16_bf16 v[80:95], v[228:231], v[240:243], v[80:95]
	s_waitcnt lgkmcnt(0)
	v_mfma_f32_32x32x16_bf16 v[64:79], v[228:231], v[244:247], v[64:79]
	s_waitcnt lgkmcnt(1)
	v_mfma_f32_32x32x16_bf16 v[48:63], v[232:235], v[240:243], v[48:63]
	s_waitcnt lgkmcnt(0)
	v_mfma_f32_32x32x16_bf16 v[32:47], v[232:235], v[244:247], v[32:47]
	s_waitcnt lgkmcnt(1)
	v_mfma_f32_32x32x16_bf16 v[16:31], v[236:239], v[240:243], v[16:31]
	s_waitcnt lgkmcnt(0)
	v_mfma_f32_32x32x16_bf16 v[0:15], v[236:239], v[244:247], v[0:15]
	s_waitcnt vmcnt(0)
	s_mul_i32 s44, s12, 0x1240
	s_add_u32 s40, s30, s44
	s_addc_u32 s41, s31, 0
	s_lshl_b32 s44, s8, 1
	s_add_u32 s40, s40, s44
	s_addc_u32 s41, s41, 0
	s_add_u32 s40, s40, 0x7157900
	s_addc_u32 s41, s41, 0
	v_and_b32_e32 v131, 15, v182
	v_lshrrev_b32_e32 v172, 4, v182
	v_lshl_add_u32 v130, v131, 3, s8
	s_movk_i32 s44, 0x920
	v_cmp_gt_u32_e64 s[42:43], s44, v130
	v_mul_u32_u24_e32 v164, 0x1240, v172
	v_lshl_add_u32 v164, v131, 4, v164
	v_add_u32_e32 v165, 0x12400, v164
	v_add_u32_e32 v166, 0x24800, v164
	v_add_u32_e32 v167, 0x36c00, v164
	v_add_u32_e32 v168, 0x92000, v164
	v_add_u32_e32 v169, 0xa4400, v164
	v_add_u32_e32 v170, 0xb6800, v164
	v_add_u32_e32 v171, 0xc8c00, v164
	v_mul_u32_u24_e32 v129, 0x110, v172
	v_lshl_add_u32 v129, v131, 4, v129
	v_lshrrev_b32_e32 v131, 7, v182
	v_bfe_u32 v172, v182, 5, 1
	v_lshlrev_b32_e32 v131, 6, v131
	v_lshl_or_b32 v131, v172, 2, v131
	v_mul_u32_u24_e32 v131, 136, v131
	v_and_b32_e32 v172, 0x5f, v182
	v_add_lshl_u32 v128, v131, v172, 1
	s_barrier
	v_cvt_pk_bf16_f32 v112, v112, v113
	v_cvt_pk_bf16_f32 v114, v114, v115
	v_cvt_pk_bf16_f32 v116, v116, v117
	v_cvt_pk_bf16_f32 v118, v118, v119
	v_cvt_pk_bf16_f32 v120, v120, v121
	v_cvt_pk_bf16_f32 v122, v122, v123
	v_cvt_pk_bf16_f32 v124, v124, v125
	v_cvt_pk_bf16_f32 v126, v126, v127
	v_cvt_pk_bf16_f32 v96, v96, v97
	v_cvt_pk_bf16_f32 v98, v98, v99
	v_cvt_pk_bf16_f32 v100, v100, v101
	v_cvt_pk_bf16_f32 v102, v102, v103
	v_cvt_pk_bf16_f32 v104, v104, v105
	v_cvt_pk_bf16_f32 v106, v106, v107
	v_cvt_pk_bf16_f32 v108, v108, v109
	v_cvt_pk_bf16_f32 v110, v110, v111
	v_cvt_pk_bf16_f32 v80, v80, v81
	v_cvt_pk_bf16_f32 v82, v82, v83
	v_cvt_pk_bf16_f32 v84, v84, v85
	v_cvt_pk_bf16_f32 v86, v86, v87
	v_cvt_pk_bf16_f32 v88, v88, v89
	v_cvt_pk_bf16_f32 v90, v90, v91
	v_cvt_pk_bf16_f32 v92, v92, v93
	v_cvt_pk_bf16_f32 v94, v94, v95
	v_cvt_pk_bf16_f32 v64, v64, v65
	v_cvt_pk_bf16_f32 v66, v66, v67
	v_cvt_pk_bf16_f32 v68, v68, v69
	v_cvt_pk_bf16_f32 v70, v70, v71
	v_cvt_pk_bf16_f32 v72, v72, v73
	v_cvt_pk_bf16_f32 v74, v74, v75
	v_cvt_pk_bf16_f32 v76, v76, v77
	v_cvt_pk_bf16_f32 v78, v78, v79
	ds_write_b16 v128, v112
	ds_write_b16_d16_hi v128, v112 offset:272
	ds_write_b16 v128, v114 offset:544
	ds_write_b16_d16_hi v128, v114 offset:816
	ds_write_b16 v128, v116 offset:2176
	ds_write_b16_d16_hi v128, v116 offset:2448
	ds_write_b16 v128, v118 offset:2720
	ds_write_b16_d16_hi v128, v118 offset:2992
	ds_write_b16 v128, v120 offset:4352
	ds_write_b16_d16_hi v128, v120 offset:4624
	ds_write_b16 v128, v122 offset:4896
	ds_write_b16_d16_hi v128, v122 offset:5168
	ds_write_b16 v128, v124 offset:6528
	ds_write_b16_d16_hi v128, v124 offset:6800
	ds_write_b16 v128, v126 offset:7072
	ds_write_b16_d16_hi v128, v126 offset:7344
	ds_write_b16 v128, v96 offset:64
	ds_write_b16_d16_hi v128, v96 offset:336
	ds_write_b16 v128, v98 offset:608
	ds_write_b16_d16_hi v128, v98 offset:880
	ds_write_b16 v128, v100 offset:2240
	ds_write_b16_d16_hi v128, v100 offset:2512
	ds_write_b16 v128, v102 offset:2784
	ds_write_b16_d16_hi v128, v102 offset:3056
	ds_write_b16 v128, v104 offset:4416
	ds_write_b16_d16_hi v128, v104 offset:4688
	ds_write_b16 v128, v106 offset:4960
	ds_write_b16_d16_hi v128, v106 offset:5232
	ds_write_b16 v128, v108 offset:6592
	ds_write_b16_d16_hi v128, v108 offset:6864
	ds_write_b16 v128, v110 offset:7136
	ds_write_b16_d16_hi v128, v110 offset:7408
	ds_write_b16 v128, v80 offset:8704
	ds_write_b16_d16_hi v128, v80 offset:8976
	ds_write_b16 v128, v82 offset:9248
	ds_write_b16_d16_hi v128, v82 offset:9520
	ds_write_b16 v128, v84 offset:10880
	ds_write_b16_d16_hi v128, v84 offset:11152
	ds_write_b16 v128, v86 offset:11424
	ds_write_b16_d16_hi v128, v86 offset:11696
	ds_write_b16 v128, v88 offset:13056
	ds_write_b16_d16_hi v128, v88 offset:13328
	ds_write_b16 v128, v90 offset:13600
	ds_write_b16_d16_hi v128, v90 offset:13872
	ds_write_b16 v128, v92 offset:15232
	ds_write_b16_d16_hi v128, v92 offset:15504
	ds_write_b16 v128, v94 offset:15776
	ds_write_b16_d16_hi v128, v94 offset:16048
	ds_write_b16 v128, v64 offset:8768
	ds_write_b16_d16_hi v128, v64 offset:9040
	ds_write_b16 v128, v66 offset:9312
	ds_write_b16_d16_hi v128, v66 offset:9584
	ds_write_b16 v128, v68 offset:10944
	ds_write_b16_d16_hi v128, v68 offset:11216
	ds_write_b16 v128, v70 offset:11488
	ds_write_b16_d16_hi v128, v70 offset:11760
	ds_write_b16 v128, v72 offset:13120
	ds_write_b16_d16_hi v128, v72 offset:13392
	ds_write_b16 v128, v74 offset:13664
	ds_write_b16_d16_hi v128, v74 offset:13936
	ds_write_b16 v128, v76 offset:15296
	ds_write_b16_d16_hi v128, v76 offset:15568
	ds_write_b16 v128, v78 offset:15840
	ds_write_b16_d16_hi v128, v78 offset:16112
	s_waitcnt lgkmcnt(0)
	s_barrier
	ds_read_b128 v[132:135], v129
	ds_read_b128 v[136:139], v129 offset:4352
	ds_read_b128 v[140:143], v129 offset:8704
	ds_read_b128 v[144:147], v129 offset:13056
	ds_read_b128 v[148:151], v129 offset:17408
	ds_read_b128 v[152:155], v129 offset:21760
	ds_read_b128 v[156:159], v129 offset:26112
	ds_read_b128 v[160:163], v129 offset:30464
	v_cvt_pk_bf16_f32 v48, v48, v49
	v_cvt_pk_bf16_f32 v50, v50, v51
	v_cvt_pk_bf16_f32 v52, v52, v53
	v_cvt_pk_bf16_f32 v54, v54, v55
	v_cvt_pk_bf16_f32 v56, v56, v57
	v_cvt_pk_bf16_f32 v58, v58, v59
	v_cvt_pk_bf16_f32 v60, v60, v61
	v_cvt_pk_bf16_f32 v62, v62, v63
	v_cvt_pk_bf16_f32 v32, v32, v33
	v_cvt_pk_bf16_f32 v34, v34, v35
	v_cvt_pk_bf16_f32 v36, v36, v37
	v_cvt_pk_bf16_f32 v38, v38, v39
	v_cvt_pk_bf16_f32 v40, v40, v41
	v_cvt_pk_bf16_f32 v42, v42, v43
	v_cvt_pk_bf16_f32 v44, v44, v45
	v_cvt_pk_bf16_f32 v46, v46, v47
	v_cvt_pk_bf16_f32 v16, v16, v17
	v_cvt_pk_bf16_f32 v18, v18, v19
	v_cvt_pk_bf16_f32 v20, v20, v21
	v_cvt_pk_bf16_f32 v22, v22, v23
	v_cvt_pk_bf16_f32 v24, v24, v25
	v_cvt_pk_bf16_f32 v26, v26, v27
	v_cvt_pk_bf16_f32 v28, v28, v29
	v_cvt_pk_bf16_f32 v30, v30, v31
	v_cvt_pk_bf16_f32 v0, v0, v1
	v_cvt_pk_bf16_f32 v2, v2, v3
	v_cvt_pk_bf16_f32 v4, v4, v5
	v_cvt_pk_bf16_f32 v6, v6, v7
	v_cvt_pk_bf16_f32 v8, v8, v9
	v_cvt_pk_bf16_f32 v10, v10, v11
	v_cvt_pk_bf16_f32 v12, v12, v13
	v_cvt_pk_bf16_f32 v14, v14, v15
	s_and_saveexec_b64 s[46:47], s[42:43]
	s_waitcnt lgkmcnt(7)
	global_store_dwordx4 v164, v[132:135], s[40:41]
	s_waitcnt lgkmcnt(6)
	global_store_dwordx4 v165, v[136:139], s[40:41]
	s_waitcnt lgkmcnt(5)
	global_store_dwordx4 v166, v[140:143], s[40:41]
	s_waitcnt lgkmcnt(4)
	global_store_dwordx4 v167, v[144:147], s[40:41]
	s_waitcnt lgkmcnt(3)
	global_store_dwordx4 v168, v[148:151], s[40:41]
	s_waitcnt lgkmcnt(2)
	global_store_dwordx4 v169, v[152:155], s[40:41]
	s_waitcnt lgkmcnt(1)
	global_store_dwordx4 v170, v[156:159], s[40:41]
	s_waitcnt lgkmcnt(0)
	global_store_dwordx4 v171, v[160:163], s[40:41]
	s_or_b64 exec, exec, s[46:47]
	s_barrier
	ds_write_b16 v128, v48
	ds_write_b16_d16_hi v128, v48 offset:272
	ds_write_b16 v128, v50 offset:544
	ds_write_b16_d16_hi v128, v50 offset:816
	ds_write_b16 v128, v52 offset:2176
	ds_write_b16_d16_hi v128, v52 offset:2448
	ds_write_b16 v128, v54 offset:2720
	ds_write_b16_d16_hi v128, v54 offset:2992
	ds_write_b16 v128, v56 offset:4352
	ds_write_b16_d16_hi v128, v56 offset:4624
	ds_write_b16 v128, v58 offset:4896
	ds_write_b16_d16_hi v128, v58 offset:5168
	ds_write_b16 v128, v60 offset:6528
	ds_write_b16_d16_hi v128, v60 offset:6800
	ds_write_b16 v128, v62 offset:7072
	ds_write_b16_d16_hi v128, v62 offset:7344
	ds_write_b16 v128, v32 offset:64
	ds_write_b16_d16_hi v128, v32 offset:336
	ds_write_b16 v128, v34 offset:608
	ds_write_b16_d16_hi v128, v34 offset:880
	ds_write_b16 v128, v36 offset:2240
	ds_write_b16_d16_hi v128, v36 offset:2512
	ds_write_b16 v128, v38 offset:2784
	ds_write_b16_d16_hi v128, v38 offset:3056
	ds_write_b16 v128, v40 offset:4416
	ds_write_b16_d16_hi v128, v40 offset:4688
	ds_write_b16 v128, v42 offset:4960
	ds_write_b16_d16_hi v128, v42 offset:5232
	ds_write_b16 v128, v44 offset:6592
	ds_write_b16_d16_hi v128, v44 offset:6864
	ds_write_b16 v128, v46 offset:7136
	ds_write_b16_d16_hi v128, v46 offset:7408
	ds_write_b16 v128, v16 offset:8704
	ds_write_b16_d16_hi v128, v16 offset:8976
	ds_write_b16 v128, v18 offset:9248
	ds_write_b16_d16_hi v128, v18 offset:9520
	ds_write_b16 v128, v20 offset:10880
	ds_write_b16_d16_hi v128, v20 offset:11152
	ds_write_b16 v128, v22 offset:11424
	ds_write_b16_d16_hi v128, v22 offset:11696
	ds_write_b16 v128, v24 offset:13056
	ds_write_b16_d16_hi v128, v24 offset:13328
	ds_write_b16 v128, v26 offset:13600
	ds_write_b16_d16_hi v128, v26 offset:13872
	ds_write_b16 v128, v28 offset:15232
	ds_write_b16_d16_hi v128, v28 offset:15504
	ds_write_b16 v128, v30 offset:15776
	ds_write_b16_d16_hi v128, v30 offset:16048
	ds_write_b16 v128, v0 offset:8768
	ds_write_b16_d16_hi v128, v0 offset:9040
	ds_write_b16 v128, v2 offset:9312
	ds_write_b16_d16_hi v128, v2 offset:9584
	ds_write_b16 v128, v4 offset:10944
	ds_write_b16_d16_hi v128, v4 offset:11216
	ds_write_b16 v128, v6 offset:11488
	ds_write_b16_d16_hi v128, v6 offset:11760
	ds_write_b16 v128, v8 offset:13120
	ds_write_b16_d16_hi v128, v8 offset:13392
	ds_write_b16 v128, v10 offset:13664
	ds_write_b16_d16_hi v128, v10 offset:13936
	ds_write_b16 v128, v12 offset:15296
	ds_write_b16_d16_hi v128, v12 offset:15568
	ds_write_b16 v128, v14 offset:15840
	ds_write_b16_d16_hi v128, v14 offset:16112
	s_waitcnt lgkmcnt(0)
	s_barrier
	ds_read_b128 v[132:135], v129
	ds_read_b128 v[136:139], v129 offset:4352
	ds_read_b128 v[140:143], v129 offset:8704
	ds_read_b128 v[144:147], v129 offset:13056
	ds_read_b128 v[148:151], v129 offset:17408
	ds_read_b128 v[152:155], v129 offset:21760
	ds_read_b128 v[156:159], v129 offset:26112
	ds_read_b128 v[160:163], v129 offset:30464
	v_add_u32_e32 v164, 0x49000, v164
	v_add_u32_e32 v165, 0x49000, v165
	v_add_u32_e32 v166, 0x49000, v166
	v_add_u32_e32 v167, 0x49000, v167
	v_add_u32_e32 v168, 0x49000, v168
	v_add_u32_e32 v169, 0x49000, v169
	v_add_u32_e32 v170, 0x49000, v170
	v_add_u32_e32 v171, 0x49000, v171
	s_and_saveexec_b64 s[46:47], s[42:43]
	s_waitcnt lgkmcnt(7)
	global_store_dwordx4 v164, v[132:135], s[40:41]
	s_waitcnt lgkmcnt(6)
	global_store_dwordx4 v165, v[136:139], s[40:41]
	s_waitcnt lgkmcnt(5)
	global_store_dwordx4 v166, v[140:143], s[40:41]
	s_waitcnt lgkmcnt(4)
	global_store_dwordx4 v167, v[144:147], s[40:41]
	s_waitcnt lgkmcnt(3)
	global_store_dwordx4 v168, v[148:151], s[40:41]
	s_waitcnt lgkmcnt(2)
	global_store_dwordx4 v169, v[152:155], s[40:41]
	s_waitcnt lgkmcnt(1)
	global_store_dwordx4 v170, v[156:159], s[40:41]
	s_waitcnt lgkmcnt(0)
	global_store_dwordx4 v171, v[160:163], s[40:41]
	s_or_b64 exec, exec, s[46:47]
	s_branch .Lmt4_tail_0

.Lv5_c_1:
	ds_write_b128 v189, v[160:163]
	ds_write_b128 v189, v[128:131] offset:4608
	ds_write_b128 v189, v[132:135] offset:9216
	ds_write_b128 v189, v[136:139] offset:13824
	ds_write_b128 v189, v[140:143] offset:18432
	ds_write_b128 v189, v[144:147] offset:23040
	ds_write_b128 v189, v[148:151] offset:27648
	ds_write_b128 v189, v[156:159] offset:32256
	ds_write_b128 v189, v[152:155] offset:36864
	ds_write_b128 v189, v[164:167] offset:41472
	ds_write_b128 v189, v[168:171] offset:46080
	ds_write_b128 v189, v[172:175] offset:50688
	global_load_dwordx4 v[160:163], v190, s[38:39]
	global_load_dwordx4 v[128:131], v191, s[38:39]
	global_load_dwordx4 v[132:135], v192, s[38:39]
	global_load_dwordx4 v[136:139], v193, s[38:39]
	global_load_dwordx4 v[140:143], v194, s[38:39]
	global_load_dwordx4 v[144:147], v195, s[38:39]
	s_waitcnt lgkmcnt(0)
	s_barrier
.LBB0_997:
	ds_read_b128 v[216:219], v188 offset:36864
	ds_read_b128 v[200:203], v187
	ds_read_b128 v[220:223], v188 offset:41472
	ds_read_b128 v[204:207], v187 offset:4608
	ds_read_b128 v[208:211], v187 offset:9216
	ds_read_b128 v[212:215], v176
	s_waitcnt lgkmcnt(4)
	v_mfma_f32_32x32x16_bf16 v[112:127], v[200:203], v[216:219], v[112:127]
	ds_read_b128 v[240:243], v188 offset:36896
	global_load_dwordx4 v[152:155], v190, s[40:41]
	s_waitcnt lgkmcnt(4)
	v_mfma_f32_32x32x16_bf16 v[96:111], v[200:203], v[220:223], v[96:111]
	ds_read_b128 v[224:227], v187 offset:32
	global_load_dwordx4 v[164:167], v191, s[40:41]
	s_waitcnt lgkmcnt(4)
	v_mfma_f32_32x32x16_bf16 v[80:95], v[204:207], v[216:219], v[80:95]
	ds_read_b128 v[244:247], v188 offset:41504
	global_load_dwordx4 v[168:171], v192, s[40:41]
	s_waitcnt lgkmcnt(5)
	v_mfma_f32_32x32x16_bf16 v[64:79], v[204:207], v[220:223], v[64:79]
	ds_read_b128 v[228:231], v187 offset:4640
	global_load_dwordx4 v[172:175], v193, s[40:41]
	s_waitcnt lgkmcnt(5)
	v_mfma_f32_32x32x16_bf16 v[48:63], v[208:211], v[216:219], v[48:63]
	ds_read_b128 v[232:235], v187 offset:9248
	global_load_dwordx4 v[148:151], v196, s[38:39]
	s_waitcnt lgkmcnt(6)
	v_mfma_f32_32x32x16_bf16 v[32:47], v[208:211], v[220:223], v[32:47]
	ds_read_b128 v[236:239], v176 offset:32
	global_load_dwordx4 v[156:159], v197, s[38:39]
	s_add_u32 s38, s38, 0x80
	s_addc_u32 s39, s39, 0
	s_add_u32 s40, s40, 0x80
	s_addc_u32 s41, s41, 0
	s_add_u32 s12, s12, 0x80
	s_waitcnt lgkmcnt(6)
	v_mfma_f32_32x32x16_bf16 v[16:31], v[212:215], v[216:219], v[16:31]
	s_waitcnt lgkmcnt(6)
	v_mfma_f32_32x32x16_bf16 v[0:15], v[212:215], v[220:223], v[0:15]
	s_waitcnt lgkmcnt(4)
	v_mfma_f32_32x32x16_bf16 v[112:127], v[224:227], v[240:243], v[112:127]
	ds_read_b128 v[200:203], v187 offset:64
	s_waitcnt lgkmcnt(4)
	v_mfma_f32_32x32x16_bf16 v[96:111], v[224:227], v[244:247], v[96:111]
	ds_read_b128 v[204:207], v187 offset:4672
	s_waitcnt lgkmcnt(4)
	v_mfma_f32_32x32x16_bf16 v[80:95], v[228:231], v[240:243], v[80:95]
	ds_read_b128 v[208:211], v187 offset:9280
	s_waitcnt lgkmcnt(5)
	v_mfma_f32_32x32x16_bf16 v[64:79], v[228:231], v[244:247], v[64:79]
	ds_read_b128 v[212:215], v176 offset:64
	s_waitcnt lgkmcnt(5)
	v_mfma_f32_32x32x16_bf16 v[48:63], v[232:235], v[240:243], v[48:63]
	ds_read_b128 v[216:219], v188 offset:36928
	s_waitcnt lgkmcnt(6)
	v_mfma_f32_32x32x16_bf16 v[32:47], v[232:235], v[244:247], v[32:47]
	ds_read_b128 v[220:223], v188 offset:41536
	s_waitcnt lgkmcnt(6)
	v_mfma_f32_32x32x16_bf16 v[16:31], v[236:239], v[240:243], v[16:31]
	s_waitcnt lgkmcnt(6)
	v_mfma_f32_32x32x16_bf16 v[0:15], v[236:239], v[244:247], v[0:15]
	s_waitcnt lgkmcnt(1)
	v_mfma_f32_32x32x16_bf16 v[112:127], v[200:203], v[216:219], v[112:127]
	ds_read_b128 v[224:227], v187 offset:96
	s_waitcnt lgkmcnt(1)
	v_mfma_f32_32x32x16_bf16 v[96:111], v[200:203], v[220:223], v[96:111]
	ds_read_b128 v[228:231], v187 offset:4704
	s_waitcnt lgkmcnt(3)
	v_mfma_f32_32x32x16_bf16 v[80:95], v[204:207], v[216:219], v[80:95]
	ds_read_b128 v[232:235], v187 offset:9312
	s_waitcnt lgkmcnt(3)
	v_mfma_f32_32x32x16_bf16 v[64:79], v[204:207], v[220:223], v[64:79]
	ds_read_b128 v[236:239], v176 offset:96
	s_waitcnt lgkmcnt(5)
	v_mfma_f32_32x32x16_bf16 v[48:63], v[208:211], v[216:219], v[48:63]
	ds_read_b128 v[240:243], v188 offset:36960
	s_waitcnt lgkmcnt(5)
	v_mfma_f32_32x32x16_bf16 v[32:47], v[208:211], v[220:223], v[32:47]
	ds_read_b128 v[244:247], v188 offset:41568
	s_waitcnt lgkmcnt(7)
	v_mfma_f32_32x32x16_bf16 v[16:31], v[212:215], v[216:219], v[16:31]
	s_waitcnt lgkmcnt(6)
	v_mfma_f32_32x32x16_bf16 v[0:15], v[212:215], v[220:223], v[0:15]
	s_waitcnt lgkmcnt(0)
	s_barrier
	s_waitcnt vmcnt(0)
	s_waitcnt lgkmcnt(1)
	v_mfma_f32_32x32x16_bf16 v[112:127], v[224:227], v[240:243], v[112:127]
	ds_write_b128 v189, v[160:163]
	ds_write_b128 v189, v[128:131] offset:4608
	s_waitcnt lgkmcnt(2)
	v_mfma_f32_32x32x16_bf16 v[96:111], v[224:227], v[244:247], v[96:111]
	ds_write_b128 v189, v[132:135] offset:9216
	global_load_dwordx4 v[160:163], v190, s[38:39]
	s_waitcnt lgkmcnt(4)
	v_mfma_f32_32x32x16_bf16 v[80:95], v[228:231], v[240:243], v[80:95]
	ds_write_b128 v189, v[136:139] offset:13824
	ds_write_b128 v189, v[140:143] offset:18432
	global_load_dwordx4 v[128:131], v191, s[38:39]
	s_waitcnt lgkmcnt(5)
	v_mfma_f32_32x32x16_bf16 v[64:79], v[228:231], v[244:247], v[64:79]
	ds_write_b128 v189, v[144:147] offset:23040
	global_load_dwordx4 v[132:135], v192, s[38:39]
	s_waitcnt lgkmcnt(7)
	v_mfma_f32_32x32x16_bf16 v[48:63], v[232:235], v[240:243], v[48:63]
	ds_write_b128 v189, v[148:151] offset:27648
	ds_write_b128 v189, v[156:159] offset:32256
	global_load_dwordx4 v[136:139], v193, s[38:39]
	s_waitcnt lgkmcnt(8)
	v_mfma_f32_32x32x16_bf16 v[32:47], v[232:235], v[244:247], v[32:47]
	ds_write_b128 v189, v[152:155] offset:36864
	global_load_dwordx4 v[140:143], v194, s[38:39]
	s_waitcnt lgkmcnt(10)
	v_mfma_f32_32x32x16_bf16 v[16:31], v[236:239], v[240:243], v[16:31]
	ds_write_b128 v189, v[164:167] offset:41472
	ds_write_b128 v189, v[168:171] offset:46080
	global_load_dwordx4 v[144:147], v195, s[38:39]
	s_waitcnt lgkmcnt(11)
	v_mfma_f32_32x32x16_bf16 v[0:15], v[236:239], v[244:247], v[0:15]
	ds_write_b128 v189, v[172:175] offset:50688
	s_waitcnt lgkmcnt(0)
	s_barrier
	s_cmpk_lg_i32 s12, 0x780
	s_cbranch_scc1 .LBB0_997
	ds_read_b128 v[216:219], v188 offset:36864
	ds_read_b128 v[200:203], v187
	ds_read_b128 v[220:223], v188 offset:41472
	ds_read_b128 v[204:207], v187 offset:4608
	ds_read_b128 v[208:211], v187 offset:9216
	ds_read_b128 v[212:215], v176
	s_waitcnt lgkmcnt(4)
	v_mfma_f32_32x32x16_bf16 v[112:127], v[200:203], v[216:219], v[112:127]
	ds_read_b128 v[240:243], v188 offset:36896
	s_waitcnt lgkmcnt(4)
	v_mfma_f32_32x32x16_bf16 v[96:111], v[200:203], v[220:223], v[96:111]
	ds_read_b128 v[224:227], v187 offset:32
	s_waitcnt lgkmcnt(4)
	v_mfma_f32_32x32x16_bf16 v[80:95], v[204:207], v[216:219], v[80:95]
	ds_read_b128 v[244:247], v188 offset:41504
	s_waitcnt lgkmcnt(5)
	v_mfma_f32_32x32x16_bf16 v[64:79], v[204:207], v[220:223], v[64:79]
	ds_read_b128 v[228:231], v187 offset:4640
	s_waitcnt lgkmcnt(5)
	v_mfma_f32_32x32x16_bf16 v[48:63], v[208:211], v[216:219], v[48:63]
	ds_read_b128 v[232:235], v187 offset:9248
	s_waitcnt lgkmcnt(6)
	v_mfma_f32_32x32x16_bf16 v[32:47], v[208:211], v[220:223], v[32:47]
	ds_read_b128 v[236:239], v176 offset:32
	s_waitcnt lgkmcnt(6)
	v_mfma_f32_32x32x16_bf16 v[16:31], v[212:215], v[216:219], v[16:31]
	s_waitcnt lgkmcnt(6)
	v_mfma_f32_32x32x16_bf16 v[0:15], v[212:215], v[220:223], v[0:15]
	s_waitcnt lgkmcnt(4)
	v_mfma_f32_32x32x16_bf16 v[112:127], v[224:227], v[240:243], v[112:127]
	ds_read_b128 v[200:203], v187 offset:64
	s_waitcnt lgkmcnt(4)
	v_mfma_f32_32x32x16_bf16 v[96:111], v[224:227], v[244:247], v[96:111]
	ds_read_b128 v[204:207], v187 offset:4672
	s_waitcnt lgkmcnt(4)
	v_mfma_f32_32x32x16_bf16 v[80:95], v[228:231], v[240:243], v[80:95]
	ds_read_b128 v[208:211], v187 offset:9280
	s_waitcnt lgkmcnt(5)
	v_mfma_f32_32x32x16_bf16 v[64:79], v[228:231], v[244:247], v[64:79]
	ds_read_b128 v[212:215], v176 offset:64
	s_waitcnt lgkmcnt(5)
	v_mfma_f32_32x32x16_bf16 v[48:63], v[232:235], v[240:243], v[48:63]
	ds_read_b128 v[216:219], v188 offset:36928
	s_waitcnt lgkmcnt(6)
	v_mfma_f32_32x32x16_bf16 v[32:47], v[232:235], v[244:247], v[32:47]
	ds_read_b128 v[220:223], v188 offset:41536
	s_waitcnt lgkmcnt(6)
	v_mfma_f32_32x32x16_bf16 v[16:31], v[236:239], v[240:243], v[16:31]
	s_waitcnt lgkmcnt(6)
	v_mfma_f32_32x32x16_bf16 v[0:15], v[236:239], v[244:247], v[0:15]
	s_waitcnt lgkmcnt(1)
	v_mfma_f32_32x32x16_bf16 v[112:127], v[200:203], v[216:219], v[112:127]
	ds_read_b128 v[224:227], v187 offset:96
	s_waitcnt lgkmcnt(1)
	v_mfma_f32_32x32x16_bf16 v[96:111], v[200:203], v[220:223], v[96:111]
	ds_read_b128 v[228:231], v187 offset:4704
	s_waitcnt lgkmcnt(3)
	v_mfma_f32_32x32x16_bf16 v[80:95], v[204:207], v[216:219], v[80:95]
	ds_read_b128 v[232:235], v187 offset:9312
	s_waitcnt lgkmcnt(3)
	v_mfma_f32_32x32x16_bf16 v[64:79], v[204:207], v[220:223], v[64:79]
	ds_read_b128 v[236:239], v176 offset:96
	s_waitcnt lgkmcnt(5)
	v_mfma_f32_32x32x16_bf16 v[48:63], v[208:211], v[216:219], v[48:63]
	ds_read_b128 v[240:243], v188 offset:36960
	s_waitcnt lgkmcnt(5)
	v_mfma_f32_32x32x16_bf16 v[32:47], v[208:211], v[220:223], v[32:47]
	ds_read_b128 v[244:247], v188 offset:41568
	s_waitcnt lgkmcnt(7)
	v_mfma_f32_32x32x16_bf16 v[16:31], v[212:215], v[216:219], v[16:31]
	s_waitcnt lgkmcnt(6)
	v_mfma_f32_32x32x16_bf16 v[0:15], v[212:215], v[220:223], v[0:15]
	s_waitcnt lgkmcnt(1)
	v_mfma_f32_32x32x16_bf16 v[112:127], v[224:227], v[240:243], v[112:127]
	s_waitcnt lgkmcnt(0)
	v_mfma_f32_32x32x16_bf16 v[96:111], v[224:227], v[244:247], v[96:111]
	s_waitcnt lgkmcnt(1)
	v_mfma_f32_32x32x16_bf16 v[80:95], v[228:231], v[240:243], v[80:95]
	s_waitcnt lgkmcnt(0)
	v_mfma_f32_32x32x16_bf16 v[64:79], v[228:231], v[244:247], v[64:79]
	s_waitcnt lgkmcnt(1)
	v_mfma_f32_32x32x16_bf16 v[48:63], v[232:235], v[240:243], v[48:63]
	s_waitcnt lgkmcnt(0)
	v_mfma_f32_32x32x16_bf16 v[32:47], v[232:235], v[244:247], v[32:47]
	s_waitcnt lgkmcnt(1)
	v_mfma_f32_32x32x16_bf16 v[16:31], v[236:239], v[240:243], v[16:31]
	s_waitcnt lgkmcnt(0)
	v_mfma_f32_32x32x16_bf16 v[0:15], v[236:239], v[244:247], v[0:15]
	s_waitcnt vmcnt(0)
	s_mul_i32 s42, s6, 0x2000
	s_add_u32 s44, s30, s42
	s_addc_u32 s45, s31, 0
	s_lshl_b32 s42, s58, 1
	s_add_u32 s44, s44, s42
	s_addc_u32 s45, s45, 0
	s_add_u32 s44, s44, 0x7157900
	s_addc_u32 s45, s45, 0
	s_mov_b32 s43, 1
	v_max_f32_e32 v112, 0, v112
	v_max_f32_e32 v113, 0, v113
	v_mul_f32_e32 v112, v112, v112
	v_mul_f32_e32 v113, v113, v113
	v_cvt_pk_bf16_f32 v190, v112, v113
	v_max_f32_e32 v114, 0, v114
	v_max_f32_e32 v115, 0, v115
	v_mul_f32_e32 v114, v114, v114
	v_mul_f32_e32 v115, v115, v115
	v_cvt_pk_bf16_f32 v191, v114, v115
	v_max_f32_e32 v116, 0, v116
	v_max_f32_e32 v117, 0, v117
	v_mul_f32_e32 v116, v116, v116
	v_mul_f32_e32 v117, v117, v117
	v_cvt_pk_bf16_f32 v192, v116, v117
	v_max_f32_e32 v118, 0, v118
	v_max_f32_e32 v119, 0, v119
	v_mul_f32_e32 v118, v118, v118
	v_mul_f32_e32 v119, v119, v119
	v_cvt_pk_bf16_f32 v193, v118, v119
	v_max_f32_e32 v120, 0, v120
	v_max_f32_e32 v121, 0, v121
	v_mul_f32_e32 v120, v120, v120
	v_mul_f32_e32 v121, v121, v121
	v_cvt_pk_bf16_f32 v194, v120, v121
	v_max_f32_e32 v122, 0, v122
	v_max_f32_e32 v123, 0, v123
	v_mul_f32_e32 v122, v122, v122
	v_mul_f32_e32 v123, v123, v123
	v_cvt_pk_bf16_f32 v195, v122, v123
	v_max_f32_e32 v124, 0, v124
	v_max_f32_e32 v125, 0, v125
	v_mul_f32_e32 v124, v124, v124
	v_mul_f32_e32 v125, v125, v125
	v_cvt_pk_bf16_f32 v196, v124, v125
	v_max_f32_e32 v126, 0, v126
	v_max_f32_e32 v127, 0, v127
	v_mul_f32_e32 v126, v126, v126
	v_mul_f32_e32 v127, v127, v127
	v_cvt_pk_bf16_f32 v197, v126, v127
	v_max_f32_e32 v96, 0, v96
	v_max_f32_e32 v97, 0, v97
	v_mul_f32_e32 v96, v96, v96
	v_mul_f32_e32 v97, v97, v97
	v_cvt_pk_bf16_f32 v198, v96, v97
	v_max_f32_e32 v98, 0, v98
	v_max_f32_e32 v99, 0, v99
	v_mul_f32_e32 v98, v98, v98
	v_mul_f32_e32 v99, v99, v99
	v_cvt_pk_bf16_f32 v199, v98, v99
	v_max_f32_e32 v100, 0, v100
	v_max_f32_e32 v101, 0, v101
	v_mul_f32_e32 v100, v100, v100
	v_mul_f32_e32 v101, v101, v101
	v_cvt_pk_bf16_f32 v200, v100, v101
	v_max_f32_e32 v102, 0, v102
	v_max_f32_e32 v103, 0, v103
	v_mul_f32_e32 v102, v102, v102
	v_mul_f32_e32 v103, v103, v103
	v_cvt_pk_bf16_f32 v201, v102, v103
	v_max_f32_e32 v104, 0, v104
	v_max_f32_e32 v105, 0, v105
	v_mul_f32_e32 v104, v104, v104
	v_mul_f32_e32 v105, v105, v105
	v_cvt_pk_bf16_f32 v202, v104, v105
	v_max_f32_e32 v106, 0, v106
	v_max_f32_e32 v107, 0, v107
	v_mul_f32_e32 v106, v106, v106
	v_mul_f32_e32 v107, v107, v107
	v_cvt_pk_bf16_f32 v203, v106, v107
	v_max_f32_e32 v108, 0, v108
	v_max_f32_e32 v109, 0, v109
	v_mul_f32_e32 v108, v108, v108
	v_mul_f32_e32 v109, v109, v109
	v_cvt_pk_bf16_f32 v204, v108, v109
	v_max_f32_e32 v110, 0, v110
	v_max_f32_e32 v111, 0, v111
	v_mul_f32_e32 v110, v110, v110
	v_mul_f32_e32 v111, v111, v111
	v_cvt_pk_bf16_f32 v205, v110, v111
	v_max_f32_e32 v80, 0, v80
	v_max_f32_e32 v81, 0, v81
	v_mul_f32_e32 v80, v80, v80
	v_mul_f32_e32 v81, v81, v81
	v_cvt_pk_bf16_f32 v206, v80, v81
	v_max_f32_e32 v82, 0, v82
	v_max_f32_e32 v83, 0, v83
	v_mul_f32_e32 v82, v82, v82
	v_mul_f32_e32 v83, v83, v83
	v_cvt_pk_bf16_f32 v207, v82, v83
	v_max_f32_e32 v84, 0, v84
	v_max_f32_e32 v85, 0, v85
	v_mul_f32_e32 v84, v84, v84
	v_mul_f32_e32 v85, v85, v85
	v_cvt_pk_bf16_f32 v208, v84, v85
	v_max_f32_e32 v86, 0, v86
	v_max_f32_e32 v87, 0, v87
	v_mul_f32_e32 v86, v86, v86
	v_mul_f32_e32 v87, v87, v87
	v_cvt_pk_bf16_f32 v209, v86, v87
	v_max_f32_e32 v88, 0, v88
	v_max_f32_e32 v89, 0, v89
	v_mul_f32_e32 v88, v88, v88
	v_mul_f32_e32 v89, v89, v89
	v_cvt_pk_bf16_f32 v210, v88, v89
	v_max_f32_e32 v90, 0, v90
	v_max_f32_e32 v91, 0, v91
	v_mul_f32_e32 v90, v90, v90
	v_mul_f32_e32 v91, v91, v91
	v_cvt_pk_bf16_f32 v211, v90, v91
	v_max_f32_e32 v92, 0, v92
	v_max_f32_e32 v93, 0, v93
	v_mul_f32_e32 v92, v92, v92
	v_mul_f32_e32 v93, v93, v93
	v_cvt_pk_bf16_f32 v212, v92, v93
	v_max_f32_e32 v94, 0, v94
	v_max_f32_e32 v95, 0, v95
	v_mul_f32_e32 v94, v94, v94
	v_mul_f32_e32 v95, v95, v95
	v_cvt_pk_bf16_f32 v213, v94, v95
	v_max_f32_e32 v64, 0, v64
	v_max_f32_e32 v65, 0, v65
	v_mul_f32_e32 v64, v64, v64
	v_mul_f32_e32 v65, v65, v65
	v_cvt_pk_bf16_f32 v214, v64, v65
	v_max_f32_e32 v66, 0, v66
	v_max_f32_e32 v67, 0, v67
	v_mul_f32_e32 v66, v66, v66
	v_mul_f32_e32 v67, v67, v67
	v_cvt_pk_bf16_f32 v215, v66, v67
	v_max_f32_e32 v68, 0, v68
	v_max_f32_e32 v69, 0, v69
	v_mul_f32_e32 v68, v68, v68
	v_mul_f32_e32 v69, v69, v69
	v_cvt_pk_bf16_f32 v216, v68, v69
	v_max_f32_e32 v70, 0, v70
	v_max_f32_e32 v71, 0, v71
	v_mul_f32_e32 v70, v70, v70
	v_mul_f32_e32 v71, v71, v71
	v_cvt_pk_bf16_f32 v217, v70, v71
	v_max_f32_e32 v72, 0, v72
	v_max_f32_e32 v73, 0, v73
	v_mul_f32_e32 v72, v72, v72
	v_mul_f32_e32 v73, v73, v73
	v_cvt_pk_bf16_f32 v218, v72, v73
	v_max_f32_e32 v74, 0, v74
	v_max_f32_e32 v75, 0, v75
	v_mul_f32_e32 v74, v74, v74
	v_mul_f32_e32 v75, v75, v75
	v_cvt_pk_bf16_f32 v219, v74, v75
	v_max_f32_e32 v76, 0, v76
	v_max_f32_e32 v77, 0, v77
	v_mul_f32_e32 v76, v76, v76
	v_mul_f32_e32 v77, v77, v77
	v_cvt_pk_bf16_f32 v220, v76, v77
	v_max_f32_e32 v78, 0, v78
	v_max_f32_e32 v79, 0, v79
	v_mul_f32_e32 v78, v78, v78
	v_mul_f32_e32 v79, v79, v79
	v_cvt_pk_bf16_f32 v221, v78, v79
	v_max_f32_e32 v48, 0, v48
	v_max_f32_e32 v49, 0, v49
	v_mul_f32_e32 v48, v48, v48
	v_mul_f32_e32 v49, v49, v49
	v_cvt_pk_bf16_f32 v222, v48, v49
	v_max_f32_e32 v50, 0, v50
	v_max_f32_e32 v51, 0, v51
	v_mul_f32_e32 v50, v50, v50
	v_mul_f32_e32 v51, v51, v51
	v_cvt_pk_bf16_f32 v223, v50, v51
	v_max_f32_e32 v52, 0, v52
	v_max_f32_e32 v53, 0, v53
	v_mul_f32_e32 v52, v52, v52
	v_mul_f32_e32 v53, v53, v53
	v_cvt_pk_bf16_f32 v224, v52, v53
	v_max_f32_e32 v54, 0, v54
	v_max_f32_e32 v55, 0, v55
	v_mul_f32_e32 v54, v54, v54
	v_mul_f32_e32 v55, v55, v55
	v_cvt_pk_bf16_f32 v225, v54, v55
	v_max_f32_e32 v56, 0, v56
	v_max_f32_e32 v57, 0, v57
	v_mul_f32_e32 v56, v56, v56
	v_mul_f32_e32 v57, v57, v57
	v_cvt_pk_bf16_f32 v226, v56, v57
	v_max_f32_e32 v58, 0, v58
	v_max_f32_e32 v59, 0, v59
	v_mul_f32_e32 v58, v58, v58
	v_mul_f32_e32 v59, v59, v59
	v_cvt_pk_bf16_f32 v227, v58, v59
	v_max_f32_e32 v60, 0, v60
	v_max_f32_e32 v61, 0, v61
	v_mul_f32_e32 v60, v60, v60
	v_mul_f32_e32 v61, v61, v61
	v_cvt_pk_bf16_f32 v228, v60, v61
	v_max_f32_e32 v62, 0, v62
	v_max_f32_e32 v63, 0, v63
	v_mul_f32_e32 v62, v62, v62
	v_mul_f32_e32 v63, v63, v63
	v_cvt_pk_bf16_f32 v229, v62, v63
	v_max_f32_e32 v32, 0, v32
	v_max_f32_e32 v33, 0, v33
	v_mul_f32_e32 v32, v32, v32
	v_mul_f32_e32 v33, v33, v33
	v_cvt_pk_bf16_f32 v230, v32, v33
	v_max_f32_e32 v34, 0, v34
	v_max_f32_e32 v35, 0, v35
	v_mul_f32_e32 v34, v34, v34
	v_mul_f32_e32 v35, v35, v35
	v_cvt_pk_bf16_f32 v231, v34, v35
	v_max_f32_e32 v36, 0, v36
	v_max_f32_e32 v37, 0, v37
	v_mul_f32_e32 v36, v36, v36
	v_mul_f32_e32 v37, v37, v37
	v_cvt_pk_bf16_f32 v232, v36, v37
	v_max_f32_e32 v38, 0, v38
	v_max_f32_e32 v39, 0, v39
	v_mul_f32_e32 v38, v38, v38
	v_mul_f32_e32 v39, v39, v39
	v_cvt_pk_bf16_f32 v233, v38, v39
	v_max_f32_e32 v40, 0, v40
	v_max_f32_e32 v41, 0, v41
	v_mul_f32_e32 v40, v40, v40
	v_mul_f32_e32 v41, v41, v41
	v_cvt_pk_bf16_f32 v234, v40, v41
	v_max_f32_e32 v42, 0, v42
	v_max_f32_e32 v43, 0, v43
	v_mul_f32_e32 v42, v42, v42
	v_mul_f32_e32 v43, v43, v43
	v_cvt_pk_bf16_f32 v235, v42, v43
	v_max_f32_e32 v44, 0, v44
	v_max_f32_e32 v45, 0, v45
	v_mul_f32_e32 v44, v44, v44
	v_mul_f32_e32 v45, v45, v45
	v_cvt_pk_bf16_f32 v236, v44, v45
	v_max_f32_e32 v46, 0, v46
	v_max_f32_e32 v47, 0, v47
	v_mul_f32_e32 v46, v46, v46
	v_mul_f32_e32 v47, v47, v47
	v_cvt_pk_bf16_f32 v237, v46, v47
	v_max_f32_e32 v16, 0, v16
	v_max_f32_e32 v17, 0, v17
	v_mul_f32_e32 v16, v16, v16
	v_mul_f32_e32 v17, v17, v17
	v_cvt_pk_bf16_f32 v238, v16, v17
	v_max_f32_e32 v18, 0, v18
	v_max_f32_e32 v19, 0, v19
	v_mul_f32_e32 v18, v18, v18
	v_mul_f32_e32 v19, v19, v19
	v_cvt_pk_bf16_f32 v239, v18, v19
	v_max_f32_e32 v20, 0, v20
	v_max_f32_e32 v21, 0, v21
	v_mul_f32_e32 v20, v20, v20
	v_mul_f32_e32 v21, v21, v21
	v_cvt_pk_bf16_f32 v240, v20, v21
	v_max_f32_e32 v22, 0, v22
	v_max_f32_e32 v23, 0, v23
	v_mul_f32_e32 v22, v22, v22
	v_mul_f32_e32 v23, v23, v23
	v_cvt_pk_bf16_f32 v241, v22, v23
	v_max_f32_e32 v24, 0, v24
	v_max_f32_e32 v25, 0, v25
	v_mul_f32_e32 v24, v24, v24
	v_mul_f32_e32 v25, v25, v25
	v_cvt_pk_bf16_f32 v242, v24, v25
	v_max_f32_e32 v26, 0, v26
	v_max_f32_e32 v27, 0, v27
	v_mul_f32_e32 v26, v26, v26
	v_mul_f32_e32 v27, v27, v27
	v_cvt_pk_bf16_f32 v243, v26, v27
	v_max_f32_e32 v28, 0, v28
	v_max_f32_e32 v29, 0, v29
	v_mul_f32_e32 v28, v28, v28
	v_mul_f32_e32 v29, v29, v29
	v_cvt_pk_bf16_f32 v244, v28, v29
	v_max_f32_e32 v30, 0, v30
	v_max_f32_e32 v31, 0, v31
	v_mul_f32_e32 v30, v30, v30
	v_mul_f32_e32 v31, v31, v31
	v_cvt_pk_bf16_f32 v245, v30, v31
	v_max_f32_e32 v0, 0, v0
	v_max_f32_e32 v1, 0, v1
	v_mul_f32_e32 v0, v0, v0
	v_mul_f32_e32 v1, v1, v1
	v_cvt_pk_bf16_f32 v246, v0, v1
	v_max_f32_e32 v2, 0, v2
	v_max_f32_e32 v3, 0, v3
	v_mul_f32_e32 v2, v2, v2
	v_mul_f32_e32 v3, v3, v3
	v_cvt_pk_bf16_f32 v247, v2, v3
	v_max_f32_e32 v4, 0, v4
	v_max_f32_e32 v5, 0, v5
	v_mul_f32_e32 v4, v4, v4
	v_mul_f32_e32 v5, v5, v5
	v_cvt_pk_bf16_f32 v248, v4, v5
	v_max_f32_e32 v6, 0, v6
	v_max_f32_e32 v7, 0, v7
	v_mul_f32_e32 v6, v6, v6
	v_mul_f32_e32 v7, v7, v7
	v_cvt_pk_bf16_f32 v249, v6, v7
	v_max_f32_e32 v8, 0, v8
	v_max_f32_e32 v9, 0, v9
	v_mul_f32_e32 v8, v8, v8
	v_mul_f32_e32 v9, v9, v9
	v_cvt_pk_bf16_f32 v250, v8, v9
	v_max_f32_e32 v10, 0, v10
	v_max_f32_e32 v11, 0, v11
	v_mul_f32_e32 v10, v10, v10
	v_mul_f32_e32 v11, v11, v11
	v_cvt_pk_bf16_f32 v251, v10, v11
	v_max_f32_e32 v12, 0, v12
	v_max_f32_e32 v13, 0, v13
	v_mul_f32_e32 v12, v12, v12
	v_mul_f32_e32 v13, v13, v13
	v_cvt_pk_bf16_f32 v252, v12, v13
	v_max_f32_e32 v14, 0, v14
	v_max_f32_e32 v15, 0, v15
	v_mul_f32_e32 v14, v14, v14
	v_mul_f32_e32 v15, v15, v15
	v_cvt_pk_bf16_f32 v253, v14, v15
	s_add_i32 s57, s57, s22
	s_add_i32 s56, s56, s22
	s_cmpk_lt_u32 s57, 0x240
	s_cbranch_scc1 .LBB0_996
	v_and_b32_e32 v3, 15, v182
	v_lshrrev_b32_e32 v4, 4, v182
	v_mul_u32_u24_e32 v2, 0x2000, v4
	v_lshl_add_u32 v2, v3, 4, v2
	v_mul_u32_u24_e32 v1, 0x110, v4
	v_lshl_add_u32 v1, v3, 4, v1
	v_lshrrev_b32_e32 v3, 7, v182
	v_bfe_u32 v4, v182, 5, 1
	v_lshlrev_b32_e32 v3, 6, v3
	v_lshl_or_b32 v3, v4, 2, v3
	v_mul_u32_u24_e32 v3, 136, v3
	v_and_b32_e32 v4, 0x5f, v182
	v_add_lshl_u32 v0, v3, v4, 1
	s_barrier
	ds_write_b16 v0, v190
	ds_write_b16_d16_hi v0, v190 offset:272
	ds_write_b16 v0, v191 offset:544
	ds_write_b16_d16_hi v0, v191 offset:816
	ds_write_b16 v0, v192 offset:2176
	ds_write_b16_d16_hi v0, v192 offset:2448
	ds_write_b16 v0, v193 offset:2720
	ds_write_b16_d16_hi v0, v193 offset:2992
	ds_write_b16 v0, v194 offset:4352
	ds_write_b16_d16_hi v0, v194 offset:4624
	ds_write_b16 v0, v195 offset:4896
	ds_write_b16_d16_hi v0, v195 offset:5168
	ds_write_b16 v0, v196 offset:6528
	ds_write_b16_d16_hi v0, v196 offset:6800
	ds_write_b16 v0, v197 offset:7072
	ds_write_b16_d16_hi v0, v197 offset:7344
	ds_write_b16 v0, v198 offset:64
	ds_write_b16_d16_hi v0, v198 offset:336
	ds_write_b16 v0, v199 offset:608
	ds_write_b16_d16_hi v0, v199 offset:880
	ds_write_b16 v0, v200 offset:2240
	ds_write_b16_d16_hi v0, v200 offset:2512
	ds_write_b16 v0, v201 offset:2784
	ds_write_b16_d16_hi v0, v201 offset:3056
	ds_write_b16 v0, v202 offset:4416
	ds_write_b16_d16_hi v0, v202 offset:4688
	ds_write_b16 v0, v203 offset:4960
	ds_write_b16_d16_hi v0, v203 offset:5232
	ds_write_b16 v0, v204 offset:6592
	ds_write_b16_d16_hi v0, v204 offset:6864
	ds_write_b16 v0, v205 offset:7136
	ds_write_b16_d16_hi v0, v205 offset:7408
	ds_write_b16 v0, v206 offset:8704
	ds_write_b16_d16_hi v0, v206 offset:8976
	ds_write_b16 v0, v207 offset:9248
	ds_write_b16_d16_hi v0, v207 offset:9520
	ds_write_b16 v0, v208 offset:10880
	ds_write_b16_d16_hi v0, v208 offset:11152
	ds_write_b16 v0, v209 offset:11424
	ds_write_b16_d16_hi v0, v209 offset:11696
	ds_write_b16 v0, v210 offset:13056
	ds_write_b16_d16_hi v0, v210 offset:13328
	ds_write_b16 v0, v211 offset:13600
	ds_write_b16_d16_hi v0, v211 offset:13872
	ds_write_b16 v0, v212 offset:15232
	ds_write_b16_d16_hi v0, v212 offset:15504
	ds_write_b16 v0, v213 offset:15776
	ds_write_b16_d16_hi v0, v213 offset:16048
	ds_write_b16 v0, v214 offset:8768
	ds_write_b16_d16_hi v0, v214 offset:9040
	ds_write_b16 v0, v215 offset:9312
	ds_write_b16_d16_hi v0, v215 offset:9584
	ds_write_b16 v0, v216 offset:10944
	ds_write_b16_d16_hi v0, v216 offset:11216
	ds_write_b16 v0, v217 offset:11488
	ds_write_b16_d16_hi v0, v217 offset:11760
	ds_write_b16 v0, v218 offset:13120
	ds_write_b16_d16_hi v0, v218 offset:13392
	ds_write_b16 v0, v219 offset:13664
	ds_write_b16_d16_hi v0, v219 offset:13936
	ds_write_b16 v0, v220 offset:15296
	ds_write_b16_d16_hi v0, v220 offset:15568
	ds_write_b16 v0, v221 offset:15840
	ds_write_b16_d16_hi v0, v221 offset:16112
	s_waitcnt lgkmcnt(0)
	s_barrier
	ds_read_b128 v[8:11], v1
	ds_read_b128 v[12:15], v1 offset:4352
	ds_read_b128 v[16:19], v1 offset:8704
	ds_read_b128 v[20:23], v1 offset:13056
	ds_read_b128 v[24:27], v1 offset:17408
	ds_read_b128 v[28:31], v1 offset:21760
	ds_read_b128 v[32:35], v1 offset:26112
	ds_read_b128 v[36:39], v1 offset:30464
	s_add_u32 s38, s44, 0x0
	s_addc_u32 s39, s45, 0
	s_waitcnt lgkmcnt(7)
	global_store_dwordx4 v2, v[8:11], s[38:39]
	s_add_u32 s38, s44, 0x20000
	s_addc_u32 s39, s45, 0
	s_waitcnt lgkmcnt(6)
	global_store_dwordx4 v2, v[12:15], s[38:39]
	s_add_u32 s38, s44, 0x40000
	s_addc_u32 s39, s45, 0
	s_waitcnt lgkmcnt(5)
	global_store_dwordx4 v2, v[16:19], s[38:39]
	s_add_u32 s38, s44, 0x60000
	s_addc_u32 s39, s45, 0
	s_waitcnt lgkmcnt(4)
	global_store_dwordx4 v2, v[20:23], s[38:39]
	s_add_u32 s38, s44, 0x100000
	s_addc_u32 s39, s45, 0
	s_waitcnt lgkmcnt(3)
	global_store_dwordx4 v2, v[24:27], s[38:39]
	s_add_u32 s38, s44, 0x120000
	s_addc_u32 s39, s45, 0
	s_waitcnt lgkmcnt(2)
	global_store_dwordx4 v2, v[28:31], s[38:39]
	s_add_u32 s38, s44, 0x140000
	s_addc_u32 s39, s45, 0
	s_waitcnt lgkmcnt(1)
	global_store_dwordx4 v2, v[32:35], s[38:39]
	s_add_u32 s38, s44, 0x160000
	s_addc_u32 s39, s45, 0
	s_waitcnt lgkmcnt(0)
	global_store_dwordx4 v2, v[36:39], s[38:39]
	s_barrier
	ds_write_b16 v0, v222
	ds_write_b16_d16_hi v0, v222 offset:272
	ds_write_b16 v0, v223 offset:544
	ds_write_b16_d16_hi v0, v223 offset:816
	ds_write_b16 v0, v224 offset:2176
	ds_write_b16_d16_hi v0, v224 offset:2448
	ds_write_b16 v0, v225 offset:2720
	ds_write_b16_d16_hi v0, v225 offset:2992
	ds_write_b16 v0, v226 offset:4352
	ds_write_b16_d16_hi v0, v226 offset:4624
	ds_write_b16 v0, v227 offset:4896
	ds_write_b16_d16_hi v0, v227 offset:5168
	ds_write_b16 v0, v228 offset:6528
	ds_write_b16_d16_hi v0, v228 offset:6800
	ds_write_b16 v0, v229 offset:7072
	ds_write_b16_d16_hi v0, v229 offset:7344
	ds_write_b16 v0, v230 offset:64
	ds_write_b16_d16_hi v0, v230 offset:336
	ds_write_b16 v0, v231 offset:608
	ds_write_b16_d16_hi v0, v231 offset:880
	ds_write_b16 v0, v232 offset:2240
	ds_write_b16_d16_hi v0, v232 offset:2512
	ds_write_b16 v0, v233 offset:2784
	ds_write_b16_d16_hi v0, v233 offset:3056
	ds_write_b16 v0, v234 offset:4416
	ds_write_b16_d16_hi v0, v234 offset:4688
	ds_write_b16 v0, v235 offset:4960
	ds_write_b16_d16_hi v0, v235 offset:5232
	ds_write_b16 v0, v236 offset:6592
	ds_write_b16_d16_hi v0, v236 offset:6864
	ds_write_b16 v0, v237 offset:7136
	ds_write_b16_d16_hi v0, v237 offset:7408
	ds_write_b16 v0, v238 offset:8704
	ds_write_b16_d16_hi v0, v238 offset:8976
	ds_write_b16 v0, v239 offset:9248
	ds_write_b16_d16_hi v0, v239 offset:9520
	ds_write_b16 v0, v240 offset:10880
	ds_write_b16_d16_hi v0, v240 offset:11152
	ds_write_b16 v0, v241 offset:11424
	ds_write_b16_d16_hi v0, v241 offset:11696
	ds_write_b16 v0, v242 offset:13056
	ds_write_b16_d16_hi v0, v242 offset:13328
	ds_write_b16 v0, v243 offset:13600
	ds_write_b16_d16_hi v0, v243 offset:13872
	ds_write_b16 v0, v244 offset:15232
	ds_write_b16_d16_hi v0, v244 offset:15504
	ds_write_b16 v0, v245 offset:15776
	ds_write_b16_d16_hi v0, v245 offset:16048
	ds_write_b16 v0, v246 offset:8768
	ds_write_b16_d16_hi v0, v246 offset:9040
	ds_write_b16 v0, v247 offset:9312
	ds_write_b16_d16_hi v0, v247 offset:9584
	ds_write_b16 v0, v248 offset:10944
	ds_write_b16_d16_hi v0, v248 offset:11216
	ds_write_b16 v0, v249 offset:11488
	ds_write_b16_d16_hi v0, v249 offset:11760
	ds_write_b16 v0, v250 offset:13120
	ds_write_b16_d16_hi v0, v250 offset:13392
	ds_write_b16 v0, v251 offset:13664
	ds_write_b16_d16_hi v0, v251 offset:13936
	ds_write_b16 v0, v252 offset:15296
	ds_write_b16_d16_hi v0, v252 offset:15568
	ds_write_b16 v0, v253 offset:15840
	ds_write_b16_d16_hi v0, v253 offset:16112
	s_waitcnt lgkmcnt(0)
	s_barrier
	ds_read_b128 v[8:11], v1
	ds_read_b128 v[12:15], v1 offset:4352
	ds_read_b128 v[16:19], v1 offset:8704
	ds_read_b128 v[20:23], v1 offset:13056
	ds_read_b128 v[24:27], v1 offset:17408
	ds_read_b128 v[28:31], v1 offset:21760
	ds_read_b128 v[32:35], v1 offset:26112
	ds_read_b128 v[36:39], v1 offset:30464
	s_add_u32 s38, s44, 0x80000
	s_addc_u32 s39, s45, 0
	s_waitcnt lgkmcnt(7)
	global_store_dwordx4 v2, v[8:11], s[38:39]
	s_add_u32 s38, s44, 0xa0000
	s_addc_u32 s39, s45, 0
	s_waitcnt lgkmcnt(6)
	global_store_dwordx4 v2, v[12:15], s[38:39]
	s_add_u32 s38, s44, 0xc0000
	s_addc_u32 s39, s45, 0
	s_waitcnt lgkmcnt(5)
	global_store_dwordx4 v2, v[16:19], s[38:39]
	s_add_u32 s38, s44, 0xe0000
	s_addc_u32 s39, s45, 0
	s_waitcnt lgkmcnt(4)
	global_store_dwordx4 v2, v[20:23], s[38:39]
	s_add_u32 s38, s44, 0x180000
	s_addc_u32 s39, s45, 0
	s_waitcnt lgkmcnt(3)
	global_store_dwordx4 v2, v[24:27], s[38:39]
	s_add_u32 s38, s44, 0x1a0000
	s_addc_u32 s39, s45, 0
	s_waitcnt lgkmcnt(2)
	global_store_dwordx4 v2, v[28:31], s[38:39]
	s_add_u32 s38, s44, 0x1c0000
	s_addc_u32 s39, s45, 0
	s_waitcnt lgkmcnt(1)
	global_store_dwordx4 v2, v[32:35], s[38:39]
	s_add_u32 s38, s44, 0x1e0000
	s_addc_u32 s39, s45, 0
	s_waitcnt lgkmcnt(0)
	global_store_dwordx4 v2, v[36:39], s[38:39]
	s_mov_b32 s43, 0
	s_branch .LBB0_989

.LBB0_1282:
	s_mul_hi_u32 s0, s56, s25
	s_mul_i32 s1, s0, s20
	s_sub_i32 s1, s56, s1
	s_add_i32 s8, s0, 1
	s_sub_i32 s12, s1, s20
	s_cmp_ge_u32 s1, s20
	s_cselect_b32 s0, s8, s0
	s_cselect_b32 s1, s12, s1
	s_add_i32 s8, s0, 1
	s_cmp_ge_u32 s1, s20
	s_cselect_b32 s1, s8, s0
	s_add_i32 s0, s1, s23
	s_mul_i32 s1, s1, s20
	s_sub_i32 s1, s56, s1
	s_add_i32 s1, s1, s19
	s_mul_i32 s8, s0, 0xe38e3900
	v_alignbit_b32 v0, s8, s8, 8
	s_cmp_lt_u32 s1, 8
	v_cmp_gt_u32_e32 vcc, s26, v0
	s_cselect_b64 s[12:13], -1, 0
	s_and_b64 s[12:13], vcc, s[12:13]
	s_and_b64 vcc, exec, s[12:13]
	s_cbranch_vccnz .LBB0_1281
	s_lshl_b32 s12, s0, 8
	s_lshl_b32 s8, s1, 7
	s_mov_b64 s[0:1], s[30:31]
	v_mov_b32_e32 v0, v177
	s_mov_b32 s13, s9
	v_mbcnt_lo_u32_b32 v0, -1, v0
	v_mbcnt_hi_u32_b32 v0, -1, v0
	v_add_u32_e32 v182, s33, v0
	s_lshl_b64 s[16:17], s[12:13], 11
	v_ashrrev_i32_e32 v0, 3, v182
	v_lshlrev_b32_e32 v1, 3, v182
	s_add_u32 s58, s14, s16
	v_and_b32_e32 v6, 56, v1
	v_lshlrev_b32_e32 v1, 11, v0
	s_addc_u32 s59, s15, s17
	v_lshl_or_b32 v176, v6, 1, v1
	v_mul_lo_u32 v7, v0, s21
	v_lshl_add_u64 v[0:1], s[58:59], 0, v[176:177]
	v_add_co_u32_e32 v2, vcc, s27, v0
	s_lshl_b64 s[60:61], s[8:9], 11
	s_nop 0
	v_addc_co_u32_e32 v3, vcc, 0, v1, vcc
	v_add_co_u32_e32 v4, vcc, s34, v0
	s_add_u32 s60, s30, s60
	s_nop 0
	v_addc_co_u32_e32 v5, vcc, 0, v1, vcc
	global_load_dwordx4 v[128:131], v[2:3], off
	global_load_dwordx4 v[132:135], v[4:5], off
	v_add_co_u32_e32 v2, vcc, s35, v0
	s_addc_u32 s61, s31, s61
	s_nop 0
	v_addc_co_u32_e32 v3, vcc, 0, v1, vcc
	v_add_co_u32_e32 v4, vcc, s36, v0
	v_lshl_add_u64 v[178:179], s[60:61], 0, v[176:177]
	s_nop 0
	v_addc_co_u32_e32 v5, vcc, 0, v1, vcc
	global_load_dwordx4 v[136:139], v[2:3], off
	global_load_dwordx4 v[144:147], v[4:5], off
	v_add_co_u32_e32 v2, vcc, s37, v0
	v_bfe_u32 v185, v182, 6, 1
	s_nop 0
	v_addc_co_u32_e32 v3, vcc, 0, v1, vcc
	v_add_co_u32_e32 v4, vcc, s38, v0
	v_and_b32_e32 v184, 31, v182
	s_nop 0
	v_addc_co_u32_e32 v5, vcc, 0, v1, vcc
	v_add_co_u32_e32 v0, vcc, s39, v0
	global_load_dwordx4 v[148:151], v[2:3], off
	global_load_dwordx4 v[152:155], v[4:5], off
	v_addc_co_u32_e32 v1, vcc, 0, v1, vcc
	v_add_co_u32_e32 v2, vcc, s27, v178
	global_load_dwordx4 v[164:167], v176, s[58:59]
	global_load_dwordx4 v[140:143], v176, s[60:61]
	v_addc_co_u32_e32 v3, vcc, 0, v179, vcc
	global_load_dwordx4 v[156:159], v[0:1], off
	global_load_dwordx4 v[160:163], v[2:3], off
	v_add_co_u32_e32 v0, vcc, s34, v178
	v_bfe_u32 v186, v182, 5, 1
	s_nop 0
	v_addc_co_u32_e32 v1, vcc, 0, v179, vcc
	v_add_co_u32_e32 v2, vcc, s35, v178
	s_add_u32 s16, s30, s16
	s_nop 0
	v_addc_co_u32_e32 v3, vcc, 0, v179, vcc
	global_load_dwordx4 v[168:171], v[0:1], off
	global_load_dwordx4 v[172:175], v[2:3], off
	v_and_b32_e32 v0, 0xfffff9f, v182
	v_lshl_or_b32 v2, v185, 6, v184
	v_mul_lo_u32 v3, v0, s40
	v_or_b32_e32 v0, 0x60, v182
	v_lshlrev_b32_e32 v1, 4, v186
	v_mul_lo_u32 v4, v0, s40
	v_mul_u32_u24_e32 v2, 0x90, v2
	s_addc_u32 s17, s31, s17
	v_mov_b32_e32 v0, 0
	v_add_lshl_u32 v189, v7, v6, 1
	v_lshl_add_u64 v[180:181], s[16:17], 0, v[176:177]
	s_mov_b64 s[16:17], 0
	v_add_u32_e32 v188, v1, v3
	v_add_u32_e32 v187, v1, v4
	v_add_u32_e32 v176, v1, v2
	v_mov_b32_e32 v1, v0
	v_mov_b32_e32 v2, v0
	v_mov_b32_e32 v3, v0
	v_mov_b32_e32 v4, v0
	v_mov_b32_e32 v5, v0
	v_mov_b32_e32 v6, v0
	v_mov_b32_e32 v7, v0
	v_mov_b32_e32 v8, v0
	v_mov_b32_e32 v9, v0
	v_mov_b32_e32 v10, v0
	v_mov_b32_e32 v11, v0
	v_mov_b32_e32 v12, v0
	v_mov_b32_e32 v13, v0
	v_mov_b32_e32 v14, v0
	v_mov_b32_e32 v15, v0
	v_mov_b32_e32 v16, v0
	v_mov_b32_e32 v17, v0
	v_mov_b32_e32 v18, v0
	v_mov_b32_e32 v19, v0
	v_mov_b32_e32 v20, v0
	v_mov_b32_e32 v21, v0
	v_mov_b32_e32 v22, v0
	v_mov_b32_e32 v23, v0
	v_mov_b32_e32 v24, v0
	v_mov_b32_e32 v25, v0
	v_mov_b32_e32 v26, v0
	v_mov_b32_e32 v27, v0
	v_mov_b32_e32 v28, v0
	v_mov_b32_e32 v29, v0
	v_mov_b32_e32 v30, v0
	v_mov_b32_e32 v31, v0
	v_mov_b32_e32 v32, v0
	v_mov_b32_e32 v33, v0
	v_mov_b32_e32 v34, v0
	v_mov_b32_e32 v35, v0
	v_mov_b32_e32 v36, v0
	v_mov_b32_e32 v37, v0
	v_mov_b32_e32 v38, v0
	v_mov_b32_e32 v39, v0
	v_mov_b32_e32 v40, v0
	v_mov_b32_e32 v41, v0
	v_mov_b32_e32 v42, v0
	v_mov_b32_e32 v43, v0
	v_mov_b32_e32 v44, v0
	v_mov_b32_e32 v45, v0
	v_mov_b32_e32 v46, v0
	v_mov_b32_e32 v47, v0
	v_mov_b32_e32 v48, v0
	v_mov_b32_e32 v49, v0
	v_mov_b32_e32 v50, v0
	v_mov_b32_e32 v51, v0
	v_mov_b32_e32 v52, v0
	v_mov_b32_e32 v53, v0
	v_mov_b32_e32 v54, v0
	v_mov_b32_e32 v55, v0
	v_mov_b32_e32 v56, v0
	v_mov_b32_e32 v57, v0
	v_mov_b32_e32 v58, v0
	v_mov_b32_e32 v59, v0
	v_mov_b32_e32 v60, v0
	v_mov_b32_e32 v61, v0
	v_mov_b32_e32 v62, v0
	v_mov_b32_e32 v63, v0
	v_mov_b32_e32 v64, v0
	v_mov_b32_e32 v65, v0
	v_mov_b32_e32 v66, v0
	v_mov_b32_e32 v67, v0
	v_mov_b32_e32 v68, v0
	v_mov_b32_e32 v69, v0
	v_mov_b32_e32 v70, v0
	v_mov_b32_e32 v71, v0
	v_mov_b32_e32 v72, v0
	v_mov_b32_e32 v73, v0
	v_mov_b32_e32 v74, v0
	v_mov_b32_e32 v75, v0
	v_mov_b32_e32 v76, v0
	v_mov_b32_e32 v77, v0
	v_mov_b32_e32 v78, v0
	v_mov_b32_e32 v79, v0
	v_mov_b32_e32 v80, v0
	v_mov_b32_e32 v81, v0
	v_mov_b32_e32 v82, v0
	v_mov_b32_e32 v83, v0
	v_mov_b32_e32 v84, v0
	v_mov_b32_e32 v85, v0
	v_mov_b32_e32 v86, v0
	v_mov_b32_e32 v87, v0
	v_mov_b32_e32 v88, v0
	v_mov_b32_e32 v89, v0
	v_mov_b32_e32 v90, v0
	v_mov_b32_e32 v91, v0
	v_mov_b32_e32 v92, v0
	v_mov_b32_e32 v93, v0
	v_mov_b32_e32 v94, v0
	v_mov_b32_e32 v95, v0
	v_mov_b32_e32 v96, v0
	v_mov_b32_e32 v97, v0
	v_mov_b32_e32 v98, v0
	v_mov_b32_e32 v99, v0
	v_mov_b32_e32 v100, v0
	v_mov_b32_e32 v101, v0
	v_mov_b32_e32 v102, v0
	v_mov_b32_e32 v103, v0
	v_mov_b32_e32 v104, v0
	v_mov_b32_e32 v105, v0
	v_mov_b32_e32 v106, v0
	v_mov_b32_e32 v107, v0
	v_mov_b32_e32 v108, v0
	v_mov_b32_e32 v109, v0
	v_mov_b32_e32 v110, v0
	v_mov_b32_e32 v111, v0
	v_mov_b32_e32 v112, v0
	v_mov_b32_e32 v113, v0
	v_mov_b32_e32 v114, v0
	v_mov_b32_e32 v115, v0
	v_mov_b32_e32 v116, v0
	v_mov_b32_e32 v117, v0
	v_mov_b32_e32 v118, v0
	v_mov_b32_e32 v119, v0
	v_mov_b32_e32 v120, v0
	v_mov_b32_e32 v121, v0
	v_mov_b32_e32 v122, v0
	v_mov_b32_e32 v123, v0
	v_mov_b32_e32 v124, v0
	v_mov_b32_e32 v125, v0
	v_mov_b32_e32 v126, v0
	v_mov_b32_e32 v127, v0
	v_readfirstlane_b32 s42, v180
	v_readfirstlane_b32 s43, v181
	v_readfirstlane_b32 s44, v178
	v_readfirstlane_b32 s45, v179
	v_lshrrev_b32_e32 v198, 3, v182
	v_and_b32_e32 v199, 7, v182
	v_lshlrev_b32_e32 v198, 11, v198
	v_lshl_or_b32 v190, v199, 4, v198
	s_lshl_b32 s41, s33, 8
	s_sub_u32 s42, s42, s41
	s_subb_u32 s43, s43, 0
	s_sub_u32 s44, s44, s41
	s_subb_u32 s45, s45, 0
	s_add_u32 s42, s42, 0x2957980
	s_addc_u32 s43, s43, 0
	s_add_u32 s44, s44, 0x80
	s_addc_u32 s45, s45, 0
	v_add_u32_e32 v191, 0x10000, v190
	v_add_u32_e32 v192, 0x20000, v190
	v_add_u32_e32 v193, 0x30000, v190
	v_add_u32_e32 v194, 0x40000, v190
	v_add_u32_e32 v195, 0x50000, v190
	v_add_u32_e32 v196, 0x60000, v190
	v_add_u32_e32 v197, 0x70000, v190
	s_waitcnt lgkmcnt(0)
	s_barrier
	s_waitcnt vmcnt(0)
	ds_write_b128 v189, v[164:167]
	ds_write_b128 v189, v[128:131] offset:4608
	ds_write_b128 v189, v[132:135] offset:9216
	ds_write_b128 v189, v[136:139] offset:13824
	ds_write_b128 v189, v[144:147] offset:18432
	ds_write_b128 v189, v[148:151] offset:23040
	ds_write_b128 v189, v[152:155] offset:27648
	ds_write_b128 v189, v[156:159] offset:32256
	ds_write_b128 v189, v[140:143] offset:36864
	ds_write_b128 v189, v[160:163] offset:41472
	ds_write_b128 v189, v[168:171] offset:46080
	ds_write_b128 v189, v[172:175] offset:50688
	global_load_dwordx4 v[164:167], v190, s[42:43]
	global_load_dwordx4 v[128:131], v191, s[42:43]
	global_load_dwordx4 v[132:135], v192, s[42:43]
	global_load_dwordx4 v[136:139], v193, s[42:43]
	global_load_dwordx4 v[144:147], v194, s[42:43]
	global_load_dwordx4 v[148:151], v195, s[42:43]
	s_waitcnt lgkmcnt(0)
	s_barrier
.LBB0_1284:
	ds_read_b128 v[216:219], v176 offset:36864
	ds_read_b128 v[200:203], v188
	ds_read_b128 v[220:223], v176 offset:41472
	ds_read_b128 v[204:207], v188 offset:4608
	ds_read_b128 v[208:211], v188 offset:9216
	ds_read_b128 v[212:215], v187
	s_waitcnt lgkmcnt(4)
	v_mfma_f32_32x32x16_bf16 v[112:127], v[200:203], v[216:219], v[112:127]
	ds_read_b128 v[240:243], v176 offset:36896
	global_load_dwordx4 v[140:143], v190, s[44:45]
	s_waitcnt lgkmcnt(4)
	v_mfma_f32_32x32x16_bf16 v[96:111], v[200:203], v[220:223], v[96:111]
	ds_read_b128 v[224:227], v188 offset:32
	global_load_dwordx4 v[160:163], v191, s[44:45]
	s_waitcnt lgkmcnt(4)
	v_mfma_f32_32x32x16_bf16 v[80:95], v[204:207], v[216:219], v[80:95]
	ds_read_b128 v[244:247], v176 offset:41504
	global_load_dwordx4 v[168:171], v192, s[44:45]
	s_waitcnt lgkmcnt(5)
	v_mfma_f32_32x32x16_bf16 v[64:79], v[204:207], v[220:223], v[64:79]
	ds_read_b128 v[228:231], v188 offset:4640
	global_load_dwordx4 v[172:175], v193, s[44:45]
	s_waitcnt lgkmcnt(5)
	v_mfma_f32_32x32x16_bf16 v[48:63], v[208:211], v[216:219], v[48:63]
	ds_read_b128 v[232:235], v188 offset:9248
	global_load_dwordx4 v[152:155], v196, s[42:43]
	s_waitcnt lgkmcnt(6)
	v_mfma_f32_32x32x16_bf16 v[32:47], v[208:211], v[220:223], v[32:47]
	ds_read_b128 v[236:239], v187 offset:32
	global_load_dwordx4 v[156:159], v197, s[42:43]
	s_add_u32 s42, s42, 0x80
	s_addc_u32 s43, s43, 0
	s_add_u32 s44, s44, 0x80
	s_addc_u32 s45, s45, 0
	s_add_u32 s16, s16, 0x80
	s_waitcnt lgkmcnt(6)
	v_mfma_f32_32x32x16_bf16 v[16:31], v[212:215], v[216:219], v[16:31]
	s_waitcnt lgkmcnt(6)
	v_mfma_f32_32x32x16_bf16 v[0:15], v[212:215], v[220:223], v[0:15]
	s_waitcnt lgkmcnt(4)
	v_mfma_f32_32x32x16_bf16 v[112:127], v[224:227], v[240:243], v[112:127]
	ds_read_b128 v[200:203], v188 offset:64
	s_waitcnt lgkmcnt(4)
	v_mfma_f32_32x32x16_bf16 v[96:111], v[224:227], v[244:247], v[96:111]
	ds_read_b128 v[204:207], v188 offset:4672
	s_waitcnt lgkmcnt(4)
	v_mfma_f32_32x32x16_bf16 v[80:95], v[228:231], v[240:243], v[80:95]
	ds_read_b128 v[208:211], v188 offset:9280
	s_waitcnt lgkmcnt(5)
	v_mfma_f32_32x32x16_bf16 v[64:79], v[228:231], v[244:247], v[64:79]
	ds_read_b128 v[212:215], v187 offset:64
	s_waitcnt lgkmcnt(5)
	v_mfma_f32_32x32x16_bf16 v[48:63], v[232:235], v[240:243], v[48:63]
	ds_read_b128 v[216:219], v176 offset:36928
	s_waitcnt lgkmcnt(6)
	v_mfma_f32_32x32x16_bf16 v[32:47], v[232:235], v[244:247], v[32:47]
	ds_read_b128 v[220:223], v176 offset:41536
	s_waitcnt lgkmcnt(6)
	v_mfma_f32_32x32x16_bf16 v[16:31], v[236:239], v[240:243], v[16:31]
	s_waitcnt lgkmcnt(6)
	v_mfma_f32_32x32x16_bf16 v[0:15], v[236:239], v[244:247], v[0:15]
	s_waitcnt lgkmcnt(1)
	v_mfma_f32_32x32x16_bf16 v[112:127], v[200:203], v[216:219], v[112:127]
	ds_read_b128 v[224:227], v188 offset:96
	s_waitcnt lgkmcnt(1)
	v_mfma_f32_32x32x16_bf16 v[96:111], v[200:203], v[220:223], v[96:111]
	ds_read_b128 v[228:231], v188 offset:4704
	s_waitcnt lgkmcnt(3)
	v_mfma_f32_32x32x16_bf16 v[80:95], v[204:207], v[216:219], v[80:95]
	ds_read_b128 v[232:235], v188 offset:9312
	s_waitcnt lgkmcnt(3)
	v_mfma_f32_32x32x16_bf16 v[64:79], v[204:207], v[220:223], v[64:79]
	ds_read_b128 v[236:239], v187 offset:96
	s_waitcnt lgkmcnt(5)
	v_mfma_f32_32x32x16_bf16 v[48:63], v[208:211], v[216:219], v[48:63]
	ds_read_b128 v[240:243], v176 offset:36960
	s_waitcnt lgkmcnt(5)
	v_mfma_f32_32x32x16_bf16 v[32:47], v[208:211], v[220:223], v[32:47]
	ds_read_b128 v[244:247], v176 offset:41568
	s_waitcnt lgkmcnt(7)
	v_mfma_f32_32x32x16_bf16 v[16:31], v[212:215], v[216:219], v[16:31]
	s_waitcnt lgkmcnt(6)
	v_mfma_f32_32x32x16_bf16 v[0:15], v[212:215], v[220:223], v[0:15]
	s_waitcnt lgkmcnt(0)
	s_barrier
	s_waitcnt vmcnt(0)
	s_waitcnt lgkmcnt(1)
	v_mfma_f32_32x32x16_bf16 v[112:127], v[224:227], v[240:243], v[112:127]
	ds_write_b128 v189, v[164:167]
	ds_write_b128 v189, v[128:131] offset:4608
	s_waitcnt lgkmcnt(2)
	v_mfma_f32_32x32x16_bf16 v[96:111], v[224:227], v[244:247], v[96:111]
	ds_write_b128 v189, v[132:135] offset:9216
	global_load_dwordx4 v[164:167], v190, s[42:43]
	s_waitcnt lgkmcnt(4)
	v_mfma_f32_32x32x16_bf16 v[80:95], v[228:231], v[240:243], v[80:95]
	ds_write_b128 v189, v[136:139] offset:13824
	ds_write_b128 v189, v[144:147] offset:18432
	global_load_dwordx4 v[128:131], v191, s[42:43]
	s_waitcnt lgkmcnt(5)
	v_mfma_f32_32x32x16_bf16 v[64:79], v[228:231], v[244:247], v[64:79]
	ds_write_b128 v189, v[148:151] offset:23040
	global_load_dwordx4 v[132:135], v192, s[42:43]
	s_waitcnt lgkmcnt(7)
	v_mfma_f32_32x32x16_bf16 v[48:63], v[232:235], v[240:243], v[48:63]
	ds_write_b128 v189, v[152:155] offset:27648
	ds_write_b128 v189, v[156:159] offset:32256
	global_load_dwordx4 v[136:139], v193, s[42:43]
	s_waitcnt lgkmcnt(8)
	v_mfma_f32_32x32x16_bf16 v[32:47], v[232:235], v[244:247], v[32:47]
	ds_write_b128 v189, v[140:143] offset:36864
	global_load_dwordx4 v[144:147], v194, s[42:43]
	s_waitcnt lgkmcnt(10)
	v_mfma_f32_32x32x16_bf16 v[16:31], v[236:239], v[240:243], v[16:31]
	ds_write_b128 v189, v[160:163] offset:41472
	ds_write_b128 v189, v[168:171] offset:46080
	global_load_dwordx4 v[148:151], v195, s[42:43]
	s_waitcnt lgkmcnt(11)
	v_mfma_f32_32x32x16_bf16 v[0:15], v[236:239], v[244:247], v[0:15]
	ds_write_b128 v189, v[172:175] offset:50688
	s_waitcnt lgkmcnt(0)
	s_barrier
	s_cmpk_lg_i32 s16, 0x780
	s_cbranch_scc1 .LBB0_1284
	ds_read_b128 v[216:219], v176 offset:36864
	ds_read_b128 v[200:203], v188
	ds_read_b128 v[220:223], v176 offset:41472
	ds_read_b128 v[204:207], v188 offset:4608
	ds_read_b128 v[208:211], v188 offset:9216
	ds_read_b128 v[212:215], v187
	s_waitcnt lgkmcnt(4)
	v_mfma_f32_32x32x16_bf16 v[112:127], v[200:203], v[216:219], v[112:127]
	ds_read_b128 v[240:243], v176 offset:36896
	s_waitcnt lgkmcnt(4)
	v_mfma_f32_32x32x16_bf16 v[96:111], v[200:203], v[220:223], v[96:111]
	ds_read_b128 v[224:227], v188 offset:32
	s_waitcnt lgkmcnt(4)
	v_mfma_f32_32x32x16_bf16 v[80:95], v[204:207], v[216:219], v[80:95]
	ds_read_b128 v[244:247], v176 offset:41504
	s_waitcnt lgkmcnt(5)
	v_mfma_f32_32x32x16_bf16 v[64:79], v[204:207], v[220:223], v[64:79]
	ds_read_b128 v[228:231], v188 offset:4640
	s_waitcnt lgkmcnt(5)
	v_mfma_f32_32x32x16_bf16 v[48:63], v[208:211], v[216:219], v[48:63]
	ds_read_b128 v[232:235], v188 offset:9248
	s_waitcnt lgkmcnt(6)
	v_mfma_f32_32x32x16_bf16 v[32:47], v[208:211], v[220:223], v[32:47]
	ds_read_b128 v[236:239], v187 offset:32
	s_waitcnt lgkmcnt(6)
	v_mfma_f32_32x32x16_bf16 v[16:31], v[212:215], v[216:219], v[16:31]
	s_waitcnt lgkmcnt(6)
	v_mfma_f32_32x32x16_bf16 v[0:15], v[212:215], v[220:223], v[0:15]
	s_waitcnt lgkmcnt(4)
	v_mfma_f32_32x32x16_bf16 v[112:127], v[224:227], v[240:243], v[112:127]
	ds_read_b128 v[200:203], v188 offset:64
	s_waitcnt lgkmcnt(4)
	v_mfma_f32_32x32x16_bf16 v[96:111], v[224:227], v[244:247], v[96:111]
	ds_read_b128 v[204:207], v188 offset:4672
	s_waitcnt lgkmcnt(4)
	v_mfma_f32_32x32x16_bf16 v[80:95], v[228:231], v[240:243], v[80:95]
	ds_read_b128 v[208:211], v188 offset:9280
	s_waitcnt lgkmcnt(5)
	v_mfma_f32_32x32x16_bf16 v[64:79], v[228:231], v[244:247], v[64:79]
	ds_read_b128 v[212:215], v187 offset:64
	s_waitcnt lgkmcnt(5)
	v_mfma_f32_32x32x16_bf16 v[48:63], v[232:235], v[240:243], v[48:63]
	ds_read_b128 v[216:219], v176 offset:36928
	s_waitcnt lgkmcnt(6)
	v_mfma_f32_32x32x16_bf16 v[32:47], v[232:235], v[244:247], v[32:47]
	ds_read_b128 v[220:223], v176 offset:41536
	s_waitcnt lgkmcnt(6)
	v_mfma_f32_32x32x16_bf16 v[16:31], v[236:239], v[240:243], v[16:31]
	s_waitcnt lgkmcnt(6)
	v_mfma_f32_32x32x16_bf16 v[0:15], v[236:239], v[244:247], v[0:15]
	s_waitcnt lgkmcnt(1)
	v_mfma_f32_32x32x16_bf16 v[112:127], v[200:203], v[216:219], v[112:127]
	ds_read_b128 v[224:227], v188 offset:96
	s_waitcnt lgkmcnt(1)
	v_mfma_f32_32x32x16_bf16 v[96:111], v[200:203], v[220:223], v[96:111]
	ds_read_b128 v[228:231], v188 offset:4704
	s_waitcnt lgkmcnt(3)
	v_mfma_f32_32x32x16_bf16 v[80:95], v[204:207], v[216:219], v[80:95]
	ds_read_b128 v[232:235], v188 offset:9312
	s_waitcnt lgkmcnt(3)
	v_mfma_f32_32x32x16_bf16 v[64:79], v[204:207], v[220:223], v[64:79]
	ds_read_b128 v[236:239], v187 offset:96
	s_waitcnt lgkmcnt(5)
	v_mfma_f32_32x32x16_bf16 v[48:63], v[208:211], v[216:219], v[48:63]
	ds_read_b128 v[240:243], v176 offset:36960
	s_waitcnt lgkmcnt(5)
	v_mfma_f32_32x32x16_bf16 v[32:47], v[208:211], v[220:223], v[32:47]
	ds_read_b128 v[244:247], v176 offset:41568
	s_waitcnt lgkmcnt(7)
	v_mfma_f32_32x32x16_bf16 v[16:31], v[212:215], v[216:219], v[16:31]
	s_waitcnt lgkmcnt(6)
	v_mfma_f32_32x32x16_bf16 v[0:15], v[212:215], v[220:223], v[0:15]
	s_waitcnt lgkmcnt(1)
	v_mfma_f32_32x32x16_bf16 v[112:127], v[224:227], v[240:243], v[112:127]
	s_waitcnt lgkmcnt(0)
	v_mfma_f32_32x32x16_bf16 v[96:111], v[224:227], v[244:247], v[96:111]
	s_waitcnt lgkmcnt(1)
	v_mfma_f32_32x32x16_bf16 v[80:95], v[228:231], v[240:243], v[80:95]
	s_waitcnt lgkmcnt(0)
	v_mfma_f32_32x32x16_bf16 v[64:79], v[228:231], v[244:247], v[64:79]
	s_waitcnt lgkmcnt(1)
	v_mfma_f32_32x32x16_bf16 v[48:63], v[232:235], v[240:243], v[48:63]
	s_waitcnt lgkmcnt(0)
	v_mfma_f32_32x32x16_bf16 v[32:47], v[232:235], v[244:247], v[32:47]
	s_waitcnt lgkmcnt(1)
	v_mfma_f32_32x32x16_bf16 v[16:31], v[236:239], v[240:243], v[16:31]
	s_waitcnt lgkmcnt(0)
	v_mfma_f32_32x32x16_bf16 v[0:15], v[236:239], v[244:247], v[0:15]
	s_waitcnt vmcnt(0)
	s_mul_i32 s41, s12, 0x1240
	s_add_u32 s42, s30, s41
	s_addc_u32 s43, s31, 0
	s_lshl_b32 s41, s8, 1
	s_add_u32 s42, s42, s41
	s_addc_u32 s43, s43, 0
	s_add_u32 s42, s42, 0x7157900
	s_addc_u32 s43, s43, 0
	v_and_b32_e32 v131, 15, v182
	v_lshrrev_b32_e32 v172, 4, v182
	v_lshl_add_u32 v130, v131, 3, s8
	s_movk_i32 s41, 0x920
	v_cmp_gt_u32_e64 s[44:45], s41, v130
	v_mul_u32_u24_e32 v164, 0x1240, v172
	v_lshl_add_u32 v164, v131, 4, v164
	v_add_u32_e32 v165, 0x12400, v164
	v_add_u32_e32 v166, 0x24800, v164
	v_add_u32_e32 v167, 0x36c00, v164
	v_add_u32_e32 v168, 0x92000, v164
	v_add_u32_e32 v169, 0xa4400, v164
	v_add_u32_e32 v170, 0xb6800, v164
	v_add_u32_e32 v171, 0xc8c00, v164
	v_mul_u32_u24_e32 v129, 0x110, v172
	v_lshl_add_u32 v129, v131, 4, v129
	v_lshrrev_b32_e32 v131, 7, v182
	v_bfe_u32 v172, v182, 5, 1
	v_lshlrev_b32_e32 v131, 6, v131
	v_lshl_or_b32 v131, v172, 2, v131
	v_mul_u32_u24_e32 v131, 136, v131
	v_and_b32_e32 v172, 0x5f, v182
	v_add_lshl_u32 v128, v131, v172, 1
	s_barrier
	v_cvt_pk_bf16_f32 v112, v112, v113
	v_cvt_pk_bf16_f32 v114, v114, v115
	v_cvt_pk_bf16_f32 v116, v116, v117
	v_cvt_pk_bf16_f32 v118, v118, v119
	v_cvt_pk_bf16_f32 v120, v120, v121
	v_cvt_pk_bf16_f32 v122, v122, v123
	v_cvt_pk_bf16_f32 v124, v124, v125
	v_cvt_pk_bf16_f32 v126, v126, v127
	v_cvt_pk_bf16_f32 v96, v96, v97
	v_cvt_pk_bf16_f32 v98, v98, v99
	v_cvt_pk_bf16_f32 v100, v100, v101
	v_cvt_pk_bf16_f32 v102, v102, v103
	v_cvt_pk_bf16_f32 v104, v104, v105
	v_cvt_pk_bf16_f32 v106, v106, v107
	v_cvt_pk_bf16_f32 v108, v108, v109
	v_cvt_pk_bf16_f32 v110, v110, v111
	v_cvt_pk_bf16_f32 v80, v80, v81
	v_cvt_pk_bf16_f32 v82, v82, v83
	v_cvt_pk_bf16_f32 v84, v84, v85
	v_cvt_pk_bf16_f32 v86, v86, v87
	v_cvt_pk_bf16_f32 v88, v88, v89
	v_cvt_pk_bf16_f32 v90, v90, v91
	v_cvt_pk_bf16_f32 v92, v92, v93
	v_cvt_pk_bf16_f32 v94, v94, v95
	v_cvt_pk_bf16_f32 v64, v64, v65
	v_cvt_pk_bf16_f32 v66, v66, v67
	v_cvt_pk_bf16_f32 v68, v68, v69
	v_cvt_pk_bf16_f32 v70, v70, v71
	v_cvt_pk_bf16_f32 v72, v72, v73
	v_cvt_pk_bf16_f32 v74, v74, v75
	v_cvt_pk_bf16_f32 v76, v76, v77
	v_cvt_pk_bf16_f32 v78, v78, v79
	ds_write_b16 v128, v112
	ds_write_b16_d16_hi v128, v112 offset:272
	ds_write_b16 v128, v114 offset:544
	ds_write_b16_d16_hi v128, v114 offset:816
	ds_write_b16 v128, v116 offset:2176
	ds_write_b16_d16_hi v128, v116 offset:2448
	ds_write_b16 v128, v118 offset:2720
	ds_write_b16_d16_hi v128, v118 offset:2992
	ds_write_b16 v128, v120 offset:4352
	ds_write_b16_d16_hi v128, v120 offset:4624
	ds_write_b16 v128, v122 offset:4896
	ds_write_b16_d16_hi v128, v122 offset:5168
	ds_write_b16 v128, v124 offset:6528
	ds_write_b16_d16_hi v128, v124 offset:6800
	ds_write_b16 v128, v126 offset:7072
	ds_write_b16_d16_hi v128, v126 offset:7344
	ds_write_b16 v128, v96 offset:64
	ds_write_b16_d16_hi v128, v96 offset:336
	ds_write_b16 v128, v98 offset:608
	ds_write_b16_d16_hi v128, v98 offset:880
	ds_write_b16 v128, v100 offset:2240
	ds_write_b16_d16_hi v128, v100 offset:2512
	ds_write_b16 v128, v102 offset:2784
	ds_write_b16_d16_hi v128, v102 offset:3056
	ds_write_b16 v128, v104 offset:4416
	ds_write_b16_d16_hi v128, v104 offset:4688
	ds_write_b16 v128, v106 offset:4960
	ds_write_b16_d16_hi v128, v106 offset:5232
	ds_write_b16 v128, v108 offset:6592
	ds_write_b16_d16_hi v128, v108 offset:6864
	ds_write_b16 v128, v110 offset:7136
	ds_write_b16_d16_hi v128, v110 offset:7408
	ds_write_b16 v128, v80 offset:8704
	ds_write_b16_d16_hi v128, v80 offset:8976
	ds_write_b16 v128, v82 offset:9248
	ds_write_b16_d16_hi v128, v82 offset:9520
	ds_write_b16 v128, v84 offset:10880
	ds_write_b16_d16_hi v128, v84 offset:11152
	ds_write_b16 v128, v86 offset:11424
	ds_write_b16_d16_hi v128, v86 offset:11696
	ds_write_b16 v128, v88 offset:13056
	ds_write_b16_d16_hi v128, v88 offset:13328
	ds_write_b16 v128, v90 offset:13600
	ds_write_b16_d16_hi v128, v90 offset:13872
	ds_write_b16 v128, v92 offset:15232
	ds_write_b16_d16_hi v128, v92 offset:15504
	ds_write_b16 v128, v94 offset:15776
	ds_write_b16_d16_hi v128, v94 offset:16048
	ds_write_b16 v128, v64 offset:8768
	ds_write_b16_d16_hi v128, v64 offset:9040
	ds_write_b16 v128, v66 offset:9312
	ds_write_b16_d16_hi v128, v66 offset:9584
	ds_write_b16 v128, v68 offset:10944
	ds_write_b16_d16_hi v128, v68 offset:11216
	ds_write_b16 v128, v70 offset:11488
	ds_write_b16_d16_hi v128, v70 offset:11760
	ds_write_b16 v128, v72 offset:13120
	ds_write_b16_d16_hi v128, v72 offset:13392
	ds_write_b16 v128, v74 offset:13664
	ds_write_b16_d16_hi v128, v74 offset:13936
	ds_write_b16 v128, v76 offset:15296
	ds_write_b16_d16_hi v128, v76 offset:15568
	ds_write_b16 v128, v78 offset:15840
	ds_write_b16_d16_hi v128, v78 offset:16112
	s_waitcnt lgkmcnt(0)
	s_barrier
	ds_read_b128 v[132:135], v129
	ds_read_b128 v[136:139], v129 offset:4352
	ds_read_b128 v[140:143], v129 offset:8704
	ds_read_b128 v[144:147], v129 offset:13056
	ds_read_b128 v[148:151], v129 offset:17408
	ds_read_b128 v[152:155], v129 offset:21760
	ds_read_b128 v[156:159], v129 offset:26112
	ds_read_b128 v[160:163], v129 offset:30464
	v_cvt_pk_bf16_f32 v48, v48, v49
	v_cvt_pk_bf16_f32 v50, v50, v51
	v_cvt_pk_bf16_f32 v52, v52, v53
	v_cvt_pk_bf16_f32 v54, v54, v55
	v_cvt_pk_bf16_f32 v56, v56, v57
	v_cvt_pk_bf16_f32 v58, v58, v59
	v_cvt_pk_bf16_f32 v60, v60, v61
	v_cvt_pk_bf16_f32 v62, v62, v63
	v_cvt_pk_bf16_f32 v32, v32, v33
	v_cvt_pk_bf16_f32 v34, v34, v35
	v_cvt_pk_bf16_f32 v36, v36, v37
	v_cvt_pk_bf16_f32 v38, v38, v39
	v_cvt_pk_bf16_f32 v40, v40, v41
	v_cvt_pk_bf16_f32 v42, v42, v43
	v_cvt_pk_bf16_f32 v44, v44, v45
	v_cvt_pk_bf16_f32 v46, v46, v47
	v_cvt_pk_bf16_f32 v16, v16, v17
	v_cvt_pk_bf16_f32 v18, v18, v19
	v_cvt_pk_bf16_f32 v20, v20, v21
	v_cvt_pk_bf16_f32 v22, v22, v23
	v_cvt_pk_bf16_f32 v24, v24, v25
	v_cvt_pk_bf16_f32 v26, v26, v27
	v_cvt_pk_bf16_f32 v28, v28, v29
	v_cvt_pk_bf16_f32 v30, v30, v31
	v_cvt_pk_bf16_f32 v0, v0, v1
	v_cvt_pk_bf16_f32 v2, v2, v3
	v_cvt_pk_bf16_f32 v4, v4, v5
	v_cvt_pk_bf16_f32 v6, v6, v7
	v_cvt_pk_bf16_f32 v8, v8, v9
	v_cvt_pk_bf16_f32 v10, v10, v11
	v_cvt_pk_bf16_f32 v12, v12, v13
	v_cvt_pk_bf16_f32 v14, v14, v15
	s_and_saveexec_b64 s[46:47], s[44:45]
	s_waitcnt lgkmcnt(7)
	global_store_dwordx4 v164, v[132:135], s[42:43]
	s_waitcnt lgkmcnt(6)
	global_store_dwordx4 v165, v[136:139], s[42:43]
	s_waitcnt lgkmcnt(5)
	global_store_dwordx4 v166, v[140:143], s[42:43]
	s_waitcnt lgkmcnt(4)
	global_store_dwordx4 v167, v[144:147], s[42:43]
	s_waitcnt lgkmcnt(3)
	global_store_dwordx4 v168, v[148:151], s[42:43]
	s_waitcnt lgkmcnt(2)
	global_store_dwordx4 v169, v[152:155], s[42:43]
	s_waitcnt lgkmcnt(1)
	global_store_dwordx4 v170, v[156:159], s[42:43]
	s_waitcnt lgkmcnt(0)
	global_store_dwordx4 v171, v[160:163], s[42:43]
	s_or_b64 exec, exec, s[46:47]
	s_barrier
	ds_write_b16 v128, v48
	ds_write_b16_d16_hi v128, v48 offset:272
	ds_write_b16 v128, v50 offset:544
	ds_write_b16_d16_hi v128, v50 offset:816
	ds_write_b16 v128, v52 offset:2176
	ds_write_b16_d16_hi v128, v52 offset:2448
	ds_write_b16 v128, v54 offset:2720
	ds_write_b16_d16_hi v128, v54 offset:2992
	ds_write_b16 v128, v56 offset:4352
	ds_write_b16_d16_hi v128, v56 offset:4624
	ds_write_b16 v128, v58 offset:4896
	ds_write_b16_d16_hi v128, v58 offset:5168
	ds_write_b16 v128, v60 offset:6528
	ds_write_b16_d16_hi v128, v60 offset:6800
	ds_write_b16 v128, v62 offset:7072
	ds_write_b16_d16_hi v128, v62 offset:7344
	ds_write_b16 v128, v32 offset:64
	ds_write_b16_d16_hi v128, v32 offset:336
	ds_write_b16 v128, v34 offset:608
	ds_write_b16_d16_hi v128, v34 offset:880
	ds_write_b16 v128, v36 offset:2240
	ds_write_b16_d16_hi v128, v36 offset:2512
	ds_write_b16 v128, v38 offset:2784
	ds_write_b16_d16_hi v128, v38 offset:3056
	ds_write_b16 v128, v40 offset:4416
	ds_write_b16_d16_hi v128, v40 offset:4688
	ds_write_b16 v128, v42 offset:4960
	ds_write_b16_d16_hi v128, v42 offset:5232
	ds_write_b16 v128, v44 offset:6592
	ds_write_b16_d16_hi v128, v44 offset:6864
	ds_write_b16 v128, v46 offset:7136
	ds_write_b16_d16_hi v128, v46 offset:7408
	ds_write_b16 v128, v16 offset:8704
	ds_write_b16_d16_hi v128, v16 offset:8976
	ds_write_b16 v128, v18 offset:9248
	ds_write_b16_d16_hi v128, v18 offset:9520
	ds_write_b16 v128, v20 offset:10880
	ds_write_b16_d16_hi v128, v20 offset:11152
	ds_write_b16 v128, v22 offset:11424
	ds_write_b16_d16_hi v128, v22 offset:11696
	ds_write_b16 v128, v24 offset:13056
	ds_write_b16_d16_hi v128, v24 offset:13328
	ds_write_b16 v128, v26 offset:13600
	ds_write_b16_d16_hi v128, v26 offset:13872
	ds_write_b16 v128, v28 offset:15232
	ds_write_b16_d16_hi v128, v28 offset:15504
	ds_write_b16 v128, v30 offset:15776
	ds_write_b16_d16_hi v128, v30 offset:16048
	ds_write_b16 v128, v0 offset:8768
	ds_write_b16_d16_hi v128, v0 offset:9040
	ds_write_b16 v128, v2 offset:9312
	ds_write_b16_d16_hi v128, v2 offset:9584
	ds_write_b16 v128, v4 offset:10944
	ds_write_b16_d16_hi v128, v4 offset:11216
	ds_write_b16 v128, v6 offset:11488
	ds_write_b16_d16_hi v128, v6 offset:11760
	ds_write_b16 v128, v8 offset:13120
	ds_write_b16_d16_hi v128, v8 offset:13392
	ds_write_b16 v128, v10 offset:13664
	ds_write_b16_d16_hi v128, v10 offset:13936
	ds_write_b16 v128, v12 offset:15296
	ds_write_b16_d16_hi v128, v12 offset:15568
	ds_write_b16 v128, v14 offset:15840
	ds_write_b16_d16_hi v128, v14 offset:16112
	s_waitcnt lgkmcnt(0)
	s_barrier
	ds_read_b128 v[132:135], v129
	ds_read_b128 v[136:139], v129 offset:4352
	ds_read_b128 v[140:143], v129 offset:8704
	ds_read_b128 v[144:147], v129 offset:13056
	ds_read_b128 v[148:151], v129 offset:17408
	ds_read_b128 v[152:155], v129 offset:21760
	ds_read_b128 v[156:159], v129 offset:26112
	ds_read_b128 v[160:163], v129 offset:30464
	v_add_u32_e32 v164, 0x49000, v164
	v_add_u32_e32 v165, 0x49000, v165
	v_add_u32_e32 v166, 0x49000, v166
	v_add_u32_e32 v167, 0x49000, v167
	v_add_u32_e32 v168, 0x49000, v168
	v_add_u32_e32 v169, 0x49000, v169
	v_add_u32_e32 v170, 0x49000, v170
	v_add_u32_e32 v171, 0x49000, v171
	s_and_saveexec_b64 s[46:47], s[44:45]
	s_waitcnt lgkmcnt(7)
	global_store_dwordx4 v164, v[132:135], s[42:43]
	s_waitcnt lgkmcnt(6)
	global_store_dwordx4 v165, v[136:139], s[42:43]
	s_waitcnt lgkmcnt(5)
	global_store_dwordx4 v166, v[140:143], s[42:43]
	s_waitcnt lgkmcnt(4)
	global_store_dwordx4 v167, v[144:147], s[42:43]
	s_waitcnt lgkmcnt(3)
	global_store_dwordx4 v168, v[148:151], s[42:43]
	s_waitcnt lgkmcnt(2)
	global_store_dwordx4 v169, v[152:155], s[42:43]
	s_waitcnt lgkmcnt(1)
	global_store_dwordx4 v170, v[156:159], s[42:43]
	s_waitcnt lgkmcnt(0)
	global_store_dwordx4 v171, v[160:163], s[42:43]
	s_or_b64 exec, exec, s[46:47]
	s_branch .LBB0_1281

.LBB0_1977:
	ds_read_b128 v[216:219], v188 offset:36864
	ds_read_b128 v[200:203], v187
	ds_read_b128 v[220:223], v188 offset:41472
	ds_read_b128 v[204:207], v187 offset:4608
	ds_read_b128 v[208:211], v187 offset:9216
	ds_read_b128 v[212:215], v176
	s_waitcnt lgkmcnt(4)
	v_mfma_f32_32x32x16_bf16 v[112:127], v[200:203], v[216:219], v[112:127]
	ds_read_b128 v[240:243], v188 offset:36896
	global_load_dwordx4 v[152:155], v190, s[40:41]
	s_waitcnt lgkmcnt(4)
	v_mfma_f32_32x32x16_bf16 v[96:111], v[200:203], v[220:223], v[96:111]
	ds_read_b128 v[224:227], v187 offset:32
	global_load_dwordx4 v[164:167], v191, s[40:41]
	s_waitcnt lgkmcnt(4)
	v_mfma_f32_32x32x16_bf16 v[80:95], v[204:207], v[216:219], v[80:95]
	ds_read_b128 v[244:247], v188 offset:41504
	global_load_dwordx4 v[168:171], v192, s[40:41]
	s_waitcnt lgkmcnt(5)
	v_mfma_f32_32x32x16_bf16 v[64:79], v[204:207], v[220:223], v[64:79]
	ds_read_b128 v[228:231], v187 offset:4640
	global_load_dwordx4 v[172:175], v193, s[40:41]
	s_waitcnt lgkmcnt(5)
	v_mfma_f32_32x32x16_bf16 v[48:63], v[208:211], v[216:219], v[48:63]
	ds_read_b128 v[232:235], v187 offset:9248
	global_load_dwordx4 v[148:151], v196, s[38:39]
	s_waitcnt lgkmcnt(6)
	v_mfma_f32_32x32x16_bf16 v[32:47], v[208:211], v[220:223], v[32:47]
	ds_read_b128 v[236:239], v176 offset:32
	global_load_dwordx4 v[156:159], v197, s[38:39]
	s_add_u32 s38, s38, 0x80
	s_addc_u32 s39, s39, 0
	s_add_u32 s40, s40, 0x80
	s_addc_u32 s41, s41, 0
	s_add_u32 s12, s12, 0x80
	s_waitcnt lgkmcnt(6)
	v_mfma_f32_32x32x16_bf16 v[16:31], v[212:215], v[216:219], v[16:31]
	s_waitcnt lgkmcnt(6)
	v_mfma_f32_32x32x16_bf16 v[0:15], v[212:215], v[220:223], v[0:15]
	s_waitcnt lgkmcnt(4)
	v_mfma_f32_32x32x16_bf16 v[112:127], v[224:227], v[240:243], v[112:127]
	ds_read_b128 v[200:203], v187 offset:64
	s_waitcnt lgkmcnt(4)
	v_mfma_f32_32x32x16_bf16 v[96:111], v[224:227], v[244:247], v[96:111]
	ds_read_b128 v[204:207], v187 offset:4672
	s_waitcnt lgkmcnt(4)
	v_mfma_f32_32x32x16_bf16 v[80:95], v[228:231], v[240:243], v[80:95]
	ds_read_b128 v[208:211], v187 offset:9280
	s_waitcnt lgkmcnt(5)
	v_mfma_f32_32x32x16_bf16 v[64:79], v[228:231], v[244:247], v[64:79]
	ds_read_b128 v[212:215], v176 offset:64
	s_waitcnt lgkmcnt(5)
	v_mfma_f32_32x32x16_bf16 v[48:63], v[232:235], v[240:243], v[48:63]
	ds_read_b128 v[216:219], v188 offset:36928
	s_waitcnt lgkmcnt(6)
	v_mfma_f32_32x32x16_bf16 v[32:47], v[232:235], v[244:247], v[32:47]
	ds_read_b128 v[220:223], v188 offset:41536
	s_waitcnt lgkmcnt(6)
	v_mfma_f32_32x32x16_bf16 v[16:31], v[236:239], v[240:243], v[16:31]
	s_waitcnt lgkmcnt(6)
	v_mfma_f32_32x32x16_bf16 v[0:15], v[236:239], v[244:247], v[0:15]
	s_waitcnt lgkmcnt(1)
	v_mfma_f32_32x32x16_bf16 v[112:127], v[200:203], v[216:219], v[112:127]
	ds_read_b128 v[224:227], v187 offset:96
	s_waitcnt lgkmcnt(1)
	v_mfma_f32_32x32x16_bf16 v[96:111], v[200:203], v[220:223], v[96:111]
	ds_read_b128 v[228:231], v187 offset:4704
	s_waitcnt lgkmcnt(3)
	v_mfma_f32_32x32x16_bf16 v[80:95], v[204:207], v[216:219], v[80:95]
	ds_read_b128 v[232:235], v187 offset:9312
	s_waitcnt lgkmcnt(3)
	v_mfma_f32_32x32x16_bf16 v[64:79], v[204:207], v[220:223], v[64:79]
	ds_read_b128 v[236:239], v176 offset:96
	s_waitcnt lgkmcnt(5)
	v_mfma_f32_32x32x16_bf16 v[48:63], v[208:211], v[216:219], v[48:63]
	ds_read_b128 v[240:243], v188 offset:36960
	s_waitcnt lgkmcnt(5)
	v_mfma_f32_32x32x16_bf16 v[32:47], v[208:211], v[220:223], v[32:47]
	ds_read_b128 v[244:247], v188 offset:41568
	s_waitcnt lgkmcnt(7)
	v_mfma_f32_32x32x16_bf16 v[16:31], v[212:215], v[216:219], v[16:31]
	s_waitcnt lgkmcnt(6)
	v_mfma_f32_32x32x16_bf16 v[0:15], v[212:215], v[220:223], v[0:15]
	s_waitcnt lgkmcnt(0)
	s_barrier
	s_waitcnt vmcnt(0)
	s_waitcnt lgkmcnt(1)
	v_mfma_f32_32x32x16_bf16 v[112:127], v[224:227], v[240:243], v[112:127]
	ds_write_b128 v189, v[160:163]
	ds_write_b128 v189, v[128:131] offset:4608
	s_waitcnt lgkmcnt(2)
	v_mfma_f32_32x32x16_bf16 v[96:111], v[224:227], v[244:247], v[96:111]
	ds_write_b128 v189, v[132:135] offset:9216
	global_load_dwordx4 v[160:163], v190, s[38:39]
	s_waitcnt lgkmcnt(4)
	v_mfma_f32_32x32x16_bf16 v[80:95], v[228:231], v[240:243], v[80:95]
	ds_write_b128 v189, v[136:139] offset:13824
	ds_write_b128 v189, v[140:143] offset:18432
	global_load_dwordx4 v[128:131], v191, s[38:39]
	s_waitcnt lgkmcnt(5)
	v_mfma_f32_32x32x16_bf16 v[64:79], v[228:231], v[244:247], v[64:79]
	ds_write_b128 v189, v[144:147] offset:23040
	global_load_dwordx4 v[132:135], v192, s[38:39]
	s_waitcnt lgkmcnt(7)
	v_mfma_f32_32x32x16_bf16 v[48:63], v[232:235], v[240:243], v[48:63]
	ds_write_b128 v189, v[148:151] offset:27648
	ds_write_b128 v189, v[156:159] offset:32256
	global_load_dwordx4 v[136:139], v193, s[38:39]
	s_waitcnt lgkmcnt(8)
	v_mfma_f32_32x32x16_bf16 v[32:47], v[232:235], v[244:247], v[32:47]
	ds_write_b128 v189, v[152:155] offset:36864
	global_load_dwordx4 v[140:143], v194, s[38:39]
	s_waitcnt lgkmcnt(10)
	v_mfma_f32_32x32x16_bf16 v[16:31], v[236:239], v[240:243], v[16:31]
	ds_write_b128 v189, v[164:167] offset:41472
	ds_write_b128 v189, v[168:171] offset:46080
	global_load_dwordx4 v[144:147], v195, s[38:39]
	s_waitcnt lgkmcnt(11)
	v_mfma_f32_32x32x16_bf16 v[0:15], v[236:239], v[244:247], v[0:15]
	ds_write_b128 v189, v[172:175] offset:50688
	s_waitcnt lgkmcnt(0)
	s_barrier
	s_cmpk_lg_i32 s12, 0x780
	s_cbranch_scc1 .LBB0_1977
	ds_read_b128 v[216:219], v188 offset:36864
	ds_read_b128 v[200:203], v187
	ds_read_b128 v[220:223], v188 offset:41472
	ds_read_b128 v[204:207], v187 offset:4608
	ds_read_b128 v[208:211], v187 offset:9216
	ds_read_b128 v[212:215], v176
	s_waitcnt lgkmcnt(4)
	v_mfma_f32_32x32x16_bf16 v[112:127], v[200:203], v[216:219], v[112:127]
	ds_read_b128 v[240:243], v188 offset:36896
	s_waitcnt lgkmcnt(4)
	v_mfma_f32_32x32x16_bf16 v[96:111], v[200:203], v[220:223], v[96:111]
	ds_read_b128 v[224:227], v187 offset:32
	s_waitcnt lgkmcnt(4)
	v_mfma_f32_32x32x16_bf16 v[80:95], v[204:207], v[216:219], v[80:95]
	ds_read_b128 v[244:247], v188 offset:41504
	s_waitcnt lgkmcnt(5)
	v_mfma_f32_32x32x16_bf16 v[64:79], v[204:207], v[220:223], v[64:79]
	ds_read_b128 v[228:231], v187 offset:4640
	s_waitcnt lgkmcnt(5)
	v_mfma_f32_32x32x16_bf16 v[48:63], v[208:211], v[216:219], v[48:63]
	ds_read_b128 v[232:235], v187 offset:9248
	s_waitcnt lgkmcnt(6)
	v_mfma_f32_32x32x16_bf16 v[32:47], v[208:211], v[220:223], v[32:47]
	ds_read_b128 v[236:239], v176 offset:32
	s_waitcnt lgkmcnt(6)
	v_mfma_f32_32x32x16_bf16 v[16:31], v[212:215], v[216:219], v[16:31]
	s_waitcnt lgkmcnt(6)
	v_mfma_f32_32x32x16_bf16 v[0:15], v[212:215], v[220:223], v[0:15]
	s_waitcnt lgkmcnt(4)
	v_mfma_f32_32x32x16_bf16 v[112:127], v[224:227], v[240:243], v[112:127]
	ds_read_b128 v[200:203], v187 offset:64
	s_waitcnt lgkmcnt(4)
	v_mfma_f32_32x32x16_bf16 v[96:111], v[224:227], v[244:247], v[96:111]
	ds_read_b128 v[204:207], v187 offset:4672
	s_waitcnt lgkmcnt(4)
	v_mfma_f32_32x32x16_bf16 v[80:95], v[228:231], v[240:243], v[80:95]
	ds_read_b128 v[208:211], v187 offset:9280
	s_waitcnt lgkmcnt(5)
	v_mfma_f32_32x32x16_bf16 v[64:79], v[228:231], v[244:247], v[64:79]
	ds_read_b128 v[212:215], v176 offset:64
	s_waitcnt lgkmcnt(5)
	v_mfma_f32_32x32x16_bf16 v[48:63], v[232:235], v[240:243], v[48:63]
	ds_read_b128 v[216:219], v188 offset:36928
	s_waitcnt lgkmcnt(6)
	v_mfma_f32_32x32x16_bf16 v[32:47], v[232:235], v[244:247], v[32:47]
	ds_read_b128 v[220:223], v188 offset:41536
	s_waitcnt lgkmcnt(6)
	v_mfma_f32_32x32x16_bf16 v[16:31], v[236:239], v[240:243], v[16:31]
	s_waitcnt lgkmcnt(6)
	v_mfma_f32_32x32x16_bf16 v[0:15], v[236:239], v[244:247], v[0:15]
	s_waitcnt lgkmcnt(1)
	v_mfma_f32_32x32x16_bf16 v[112:127], v[200:203], v[216:219], v[112:127]
	ds_read_b128 v[224:227], v187 offset:96
	s_waitcnt lgkmcnt(1)
	v_mfma_f32_32x32x16_bf16 v[96:111], v[200:203], v[220:223], v[96:111]
	ds_read_b128 v[228:231], v187 offset:4704
	s_waitcnt lgkmcnt(3)
	v_mfma_f32_32x32x16_bf16 v[80:95], v[204:207], v[216:219], v[80:95]
	ds_read_b128 v[232:235], v187 offset:9312
	s_waitcnt lgkmcnt(3)
	v_mfma_f32_32x32x16_bf16 v[64:79], v[204:207], v[220:223], v[64:79]
	ds_read_b128 v[236:239], v176 offset:96
	s_waitcnt lgkmcnt(5)
	v_mfma_f32_32x32x16_bf16 v[48:63], v[208:211], v[216:219], v[48:63]
	ds_read_b128 v[240:243], v188 offset:36960
	s_waitcnt lgkmcnt(5)
	v_mfma_f32_32x32x16_bf16 v[32:47], v[208:211], v[220:223], v[32:47]
	ds_read_b128 v[244:247], v188 offset:41568
	s_waitcnt lgkmcnt(7)
	v_mfma_f32_32x32x16_bf16 v[16:31], v[212:215], v[216:219], v[16:31]
	s_waitcnt lgkmcnt(6)
	v_mfma_f32_32x32x16_bf16 v[0:15], v[212:215], v[220:223], v[0:15]
	s_waitcnt lgkmcnt(1)
	v_mfma_f32_32x32x16_bf16 v[112:127], v[224:227], v[240:243], v[112:127]
	s_waitcnt lgkmcnt(0)
	v_mfma_f32_32x32x16_bf16 v[96:111], v[224:227], v[244:247], v[96:111]
	s_waitcnt lgkmcnt(1)
	v_mfma_f32_32x32x16_bf16 v[80:95], v[228:231], v[240:243], v[80:95]
	s_waitcnt lgkmcnt(0)
	v_mfma_f32_32x32x16_bf16 v[64:79], v[228:231], v[244:247], v[64:79]
	s_waitcnt lgkmcnt(1)
	v_mfma_f32_32x32x16_bf16 v[48:63], v[232:235], v[240:243], v[48:63]
	s_waitcnt lgkmcnt(0)
	v_mfma_f32_32x32x16_bf16 v[32:47], v[232:235], v[244:247], v[32:47]
	s_waitcnt lgkmcnt(1)
	v_mfma_f32_32x32x16_bf16 v[16:31], v[236:239], v[240:243], v[16:31]
	s_waitcnt lgkmcnt(0)
	v_mfma_f32_32x32x16_bf16 v[0:15], v[236:239], v[244:247], v[0:15]
	s_waitcnt vmcnt(0)
	s_mul_i32 s42, s6, 0x2000
	s_add_u32 s44, s30, s42
	s_addc_u32 s45, s31, 0
	s_lshl_b32 s42, s58, 1
	s_add_u32 s44, s44, s42
	s_addc_u32 s45, s45, 0
	s_add_u32 s44, s44, 0x7157900
	s_addc_u32 s45, s45, 0
	s_mov_b32 s43, 1
	v_max_f32_e32 v112, 0, v112
	v_max_f32_e32 v113, 0, v113
	v_mul_f32_e32 v112, v112, v112
	v_mul_f32_e32 v113, v113, v113
	v_cvt_pk_bf16_f32 v190, v112, v113
	v_max_f32_e32 v114, 0, v114
	v_max_f32_e32 v115, 0, v115
	v_mul_f32_e32 v114, v114, v114
	v_mul_f32_e32 v115, v115, v115
	v_cvt_pk_bf16_f32 v191, v114, v115
	v_max_f32_e32 v116, 0, v116
	v_max_f32_e32 v117, 0, v117
	v_mul_f32_e32 v116, v116, v116
	v_mul_f32_e32 v117, v117, v117
	v_cvt_pk_bf16_f32 v192, v116, v117
	v_max_f32_e32 v118, 0, v118
	v_max_f32_e32 v119, 0, v119
	v_mul_f32_e32 v118, v118, v118
	v_mul_f32_e32 v119, v119, v119
	v_cvt_pk_bf16_f32 v193, v118, v119
	v_max_f32_e32 v120, 0, v120
	v_max_f32_e32 v121, 0, v121
	v_mul_f32_e32 v120, v120, v120
	v_mul_f32_e32 v121, v121, v121
	v_cvt_pk_bf16_f32 v194, v120, v121
	v_max_f32_e32 v122, 0, v122
	v_max_f32_e32 v123, 0, v123
	v_mul_f32_e32 v122, v122, v122
	v_mul_f32_e32 v123, v123, v123
	v_cvt_pk_bf16_f32 v195, v122, v123
	v_max_f32_e32 v124, 0, v124
	v_max_f32_e32 v125, 0, v125
	v_mul_f32_e32 v124, v124, v124
	v_mul_f32_e32 v125, v125, v125
	v_cvt_pk_bf16_f32 v196, v124, v125
	v_max_f32_e32 v126, 0, v126
	v_max_f32_e32 v127, 0, v127
	v_mul_f32_e32 v126, v126, v126
	v_mul_f32_e32 v127, v127, v127
	v_cvt_pk_bf16_f32 v197, v126, v127
	v_max_f32_e32 v96, 0, v96
	v_max_f32_e32 v97, 0, v97
	v_mul_f32_e32 v96, v96, v96
	v_mul_f32_e32 v97, v97, v97
	v_cvt_pk_bf16_f32 v198, v96, v97
	v_max_f32_e32 v98, 0, v98
	v_max_f32_e32 v99, 0, v99
	v_mul_f32_e32 v98, v98, v98
	v_mul_f32_e32 v99, v99, v99
	v_cvt_pk_bf16_f32 v199, v98, v99
	v_max_f32_e32 v100, 0, v100
	v_max_f32_e32 v101, 0, v101
	v_mul_f32_e32 v100, v100, v100
	v_mul_f32_e32 v101, v101, v101
	v_cvt_pk_bf16_f32 v200, v100, v101
	v_max_f32_e32 v102, 0, v102
	v_max_f32_e32 v103, 0, v103
	v_mul_f32_e32 v102, v102, v102
	v_mul_f32_e32 v103, v103, v103
	v_cvt_pk_bf16_f32 v201, v102, v103
	v_max_f32_e32 v104, 0, v104
	v_max_f32_e32 v105, 0, v105
	v_mul_f32_e32 v104, v104, v104
	v_mul_f32_e32 v105, v105, v105
	v_cvt_pk_bf16_f32 v202, v104, v105
	v_max_f32_e32 v106, 0, v106
	v_max_f32_e32 v107, 0, v107
	v_mul_f32_e32 v106, v106, v106
	v_mul_f32_e32 v107, v107, v107
	v_cvt_pk_bf16_f32 v203, v106, v107
	v_max_f32_e32 v108, 0, v108
	v_max_f32_e32 v109, 0, v109
	v_mul_f32_e32 v108, v108, v108
	v_mul_f32_e32 v109, v109, v109
	v_cvt_pk_bf16_f32 v204, v108, v109
	v_max_f32_e32 v110, 0, v110
	v_max_f32_e32 v111, 0, v111
	v_mul_f32_e32 v110, v110, v110
	v_mul_f32_e32 v111, v111, v111
	v_cvt_pk_bf16_f32 v205, v110, v111
	v_max_f32_e32 v80, 0, v80
	v_max_f32_e32 v81, 0, v81
	v_mul_f32_e32 v80, v80, v80
	v_mul_f32_e32 v81, v81, v81
	v_cvt_pk_bf16_f32 v206, v80, v81
	v_max_f32_e32 v82, 0, v82
	v_max_f32_e32 v83, 0, v83
	v_mul_f32_e32 v82, v82, v82
	v_mul_f32_e32 v83, v83, v83
	v_cvt_pk_bf16_f32 v207, v82, v83
	v_max_f32_e32 v84, 0, v84
	v_max_f32_e32 v85, 0, v85
	v_mul_f32_e32 v84, v84, v84
	v_mul_f32_e32 v85, v85, v85
	v_cvt_pk_bf16_f32 v208, v84, v85
	v_max_f32_e32 v86, 0, v86
	v_max_f32_e32 v87, 0, v87
	v_mul_f32_e32 v86, v86, v86
	v_mul_f32_e32 v87, v87, v87
	v_cvt_pk_bf16_f32 v209, v86, v87
	v_max_f32_e32 v88, 0, v88
	v_max_f32_e32 v89, 0, v89
	v_mul_f32_e32 v88, v88, v88
	v_mul_f32_e32 v89, v89, v89
	v_cvt_pk_bf16_f32 v210, v88, v89
	v_max_f32_e32 v90, 0, v90
	v_max_f32_e32 v91, 0, v91
	v_mul_f32_e32 v90, v90, v90
	v_mul_f32_e32 v91, v91, v91
	v_cvt_pk_bf16_f32 v211, v90, v91
	v_max_f32_e32 v92, 0, v92
	v_max_f32_e32 v93, 0, v93
	v_mul_f32_e32 v92, v92, v92
	v_mul_f32_e32 v93, v93, v93
	v_cvt_pk_bf16_f32 v212, v92, v93
	v_max_f32_e32 v94, 0, v94
	v_max_f32_e32 v95, 0, v95
	v_mul_f32_e32 v94, v94, v94
	v_mul_f32_e32 v95, v95, v95
	v_cvt_pk_bf16_f32 v213, v94, v95
	v_max_f32_e32 v64, 0, v64
	v_max_f32_e32 v65, 0, v65
	v_mul_f32_e32 v64, v64, v64
	v_mul_f32_e32 v65, v65, v65
	v_cvt_pk_bf16_f32 v214, v64, v65
	v_max_f32_e32 v66, 0, v66
	v_max_f32_e32 v67, 0, v67
	v_mul_f32_e32 v66, v66, v66
	v_mul_f32_e32 v67, v67, v67
	v_cvt_pk_bf16_f32 v215, v66, v67
	v_max_f32_e32 v68, 0, v68
	v_max_f32_e32 v69, 0, v69
	v_mul_f32_e32 v68, v68, v68
	v_mul_f32_e32 v69, v69, v69
	v_cvt_pk_bf16_f32 v216, v68, v69
	v_max_f32_e32 v70, 0, v70
	v_max_f32_e32 v71, 0, v71
	v_mul_f32_e32 v70, v70, v70
	v_mul_f32_e32 v71, v71, v71
	v_cvt_pk_bf16_f32 v217, v70, v71
	v_max_f32_e32 v72, 0, v72
	v_max_f32_e32 v73, 0, v73
	v_mul_f32_e32 v72, v72, v72
	v_mul_f32_e32 v73, v73, v73
	v_cvt_pk_bf16_f32 v218, v72, v73
	v_max_f32_e32 v74, 0, v74
	v_max_f32_e32 v75, 0, v75
	v_mul_f32_e32 v74, v74, v74
	v_mul_f32_e32 v75, v75, v75
	v_cvt_pk_bf16_f32 v219, v74, v75
	v_max_f32_e32 v76, 0, v76
	v_max_f32_e32 v77, 0, v77
	v_mul_f32_e32 v76, v76, v76
	v_mul_f32_e32 v77, v77, v77
	v_cvt_pk_bf16_f32 v220, v76, v77
	v_max_f32_e32 v78, 0, v78
	v_max_f32_e32 v79, 0, v79
	v_mul_f32_e32 v78, v78, v78
	v_mul_f32_e32 v79, v79, v79
	v_cvt_pk_bf16_f32 v221, v78, v79
	v_max_f32_e32 v48, 0, v48
	v_max_f32_e32 v49, 0, v49
	v_mul_f32_e32 v48, v48, v48
	v_mul_f32_e32 v49, v49, v49
	v_cvt_pk_bf16_f32 v222, v48, v49
	v_max_f32_e32 v50, 0, v50
	v_max_f32_e32 v51, 0, v51
	v_mul_f32_e32 v50, v50, v50
	v_mul_f32_e32 v51, v51, v51
	v_cvt_pk_bf16_f32 v223, v50, v51
	v_max_f32_e32 v52, 0, v52
	v_max_f32_e32 v53, 0, v53
	v_mul_f32_e32 v52, v52, v52
	v_mul_f32_e32 v53, v53, v53
	v_cvt_pk_bf16_f32 v224, v52, v53
	v_max_f32_e32 v54, 0, v54
	v_max_f32_e32 v55, 0, v55
	v_mul_f32_e32 v54, v54, v54
	v_mul_f32_e32 v55, v55, v55
	v_cvt_pk_bf16_f32 v225, v54, v55
	v_max_f32_e32 v56, 0, v56
	v_max_f32_e32 v57, 0, v57
	v_mul_f32_e32 v56, v56, v56
	v_mul_f32_e32 v57, v57, v57
	v_cvt_pk_bf16_f32 v226, v56, v57
	v_max_f32_e32 v58, 0, v58
	v_max_f32_e32 v59, 0, v59
	v_mul_f32_e32 v58, v58, v58
	v_mul_f32_e32 v59, v59, v59
	v_cvt_pk_bf16_f32 v227, v58, v59
	v_max_f32_e32 v60, 0, v60
	v_max_f32_e32 v61, 0, v61
	v_mul_f32_e32 v60, v60, v60
	v_mul_f32_e32 v61, v61, v61
	v_cvt_pk_bf16_f32 v228, v60, v61
	v_max_f32_e32 v62, 0, v62
	v_max_f32_e32 v63, 0, v63
	v_mul_f32_e32 v62, v62, v62
	v_mul_f32_e32 v63, v63, v63
	v_cvt_pk_bf16_f32 v229, v62, v63
	v_max_f32_e32 v32, 0, v32
	v_max_f32_e32 v33, 0, v33
	v_mul_f32_e32 v32, v32, v32
	v_mul_f32_e32 v33, v33, v33
	v_cvt_pk_bf16_f32 v230, v32, v33
	v_max_f32_e32 v34, 0, v34
	v_max_f32_e32 v35, 0, v35
	v_mul_f32_e32 v34, v34, v34
	v_mul_f32_e32 v35, v35, v35
	v_cvt_pk_bf16_f32 v231, v34, v35
	v_max_f32_e32 v36, 0, v36
	v_max_f32_e32 v37, 0, v37
	v_mul_f32_e32 v36, v36, v36
	v_mul_f32_e32 v37, v37, v37
	v_cvt_pk_bf16_f32 v232, v36, v37
	v_max_f32_e32 v38, 0, v38
	v_max_f32_e32 v39, 0, v39
	v_mul_f32_e32 v38, v38, v38
	v_mul_f32_e32 v39, v39, v39
	v_cvt_pk_bf16_f32 v233, v38, v39
	v_max_f32_e32 v40, 0, v40
	v_max_f32_e32 v41, 0, v41
	v_mul_f32_e32 v40, v40, v40
	v_mul_f32_e32 v41, v41, v41
	v_cvt_pk_bf16_f32 v234, v40, v41
	v_max_f32_e32 v42, 0, v42
	v_max_f32_e32 v43, 0, v43
	v_mul_f32_e32 v42, v42, v42
	v_mul_f32_e32 v43, v43, v43
	v_cvt_pk_bf16_f32 v235, v42, v43
	v_max_f32_e32 v44, 0, v44
	v_max_f32_e32 v45, 0, v45
	v_mul_f32_e32 v44, v44, v44
	v_mul_f32_e32 v45, v45, v45
	v_cvt_pk_bf16_f32 v236, v44, v45
	v_max_f32_e32 v46, 0, v46
	v_max_f32_e32 v47, 0, v47
	v_mul_f32_e32 v46, v46, v46
	v_mul_f32_e32 v47, v47, v47
	v_cvt_pk_bf16_f32 v237, v46, v47
	v_max_f32_e32 v16, 0, v16
	v_max_f32_e32 v17, 0, v17
	v_mul_f32_e32 v16, v16, v16
	v_mul_f32_e32 v17, v17, v17
	v_cvt_pk_bf16_f32 v238, v16, v17
	v_max_f32_e32 v18, 0, v18
	v_max_f32_e32 v19, 0, v19
	v_mul_f32_e32 v18, v18, v18
	v_mul_f32_e32 v19, v19, v19
	v_cvt_pk_bf16_f32 v239, v18, v19
	v_max_f32_e32 v20, 0, v20
	v_max_f32_e32 v21, 0, v21
	v_mul_f32_e32 v20, v20, v20
	v_mul_f32_e32 v21, v21, v21
	v_cvt_pk_bf16_f32 v240, v20, v21
	v_max_f32_e32 v22, 0, v22
	v_max_f32_e32 v23, 0, v23
	v_mul_f32_e32 v22, v22, v22
	v_mul_f32_e32 v23, v23, v23
	v_cvt_pk_bf16_f32 v241, v22, v23
	v_max_f32_e32 v24, 0, v24
	v_max_f32_e32 v25, 0, v25
	v_mul_f32_e32 v24, v24, v24
	v_mul_f32_e32 v25, v25, v25
	v_cvt_pk_bf16_f32 v242, v24, v25
	v_max_f32_e32 v26, 0, v26
	v_max_f32_e32 v27, 0, v27
	v_mul_f32_e32 v26, v26, v26
	v_mul_f32_e32 v27, v27, v27
	v_cvt_pk_bf16_f32 v243, v26, v27
	v_max_f32_e32 v28, 0, v28
	v_max_f32_e32 v29, 0, v29
	v_mul_f32_e32 v28, v28, v28
	v_mul_f32_e32 v29, v29, v29
	v_cvt_pk_bf16_f32 v244, v28, v29
	v_max_f32_e32 v30, 0, v30
	v_max_f32_e32 v31, 0, v31
	v_mul_f32_e32 v30, v30, v30
	v_mul_f32_e32 v31, v31, v31
	v_cvt_pk_bf16_f32 v245, v30, v31
	v_max_f32_e32 v0, 0, v0
	v_max_f32_e32 v1, 0, v1
	v_mul_f32_e32 v0, v0, v0
	v_mul_f32_e32 v1, v1, v1
	v_cvt_pk_bf16_f32 v246, v0, v1
	v_max_f32_e32 v2, 0, v2
	v_max_f32_e32 v3, 0, v3
	v_mul_f32_e32 v2, v2, v2
	v_mul_f32_e32 v3, v3, v3
	v_cvt_pk_bf16_f32 v247, v2, v3
	v_max_f32_e32 v4, 0, v4
	v_max_f32_e32 v5, 0, v5
	v_mul_f32_e32 v4, v4, v4
	v_mul_f32_e32 v5, v5, v5
	v_cvt_pk_bf16_f32 v248, v4, v5
	v_max_f32_e32 v6, 0, v6
	v_max_f32_e32 v7, 0, v7
	v_mul_f32_e32 v6, v6, v6
	v_mul_f32_e32 v7, v7, v7
	v_cvt_pk_bf16_f32 v249, v6, v7
	v_max_f32_e32 v8, 0, v8
	v_max_f32_e32 v9, 0, v9
	v_mul_f32_e32 v8, v8, v8
	v_mul_f32_e32 v9, v9, v9
	v_cvt_pk_bf16_f32 v250, v8, v9
	v_max_f32_e32 v10, 0, v10
	v_max_f32_e32 v11, 0, v11
	v_mul_f32_e32 v10, v10, v10
	v_mul_f32_e32 v11, v11, v11
	v_cvt_pk_bf16_f32 v251, v10, v11
	v_max_f32_e32 v12, 0, v12
	v_max_f32_e32 v13, 0, v13
	v_mul_f32_e32 v12, v12, v12
	v_mul_f32_e32 v13, v13, v13
	v_cvt_pk_bf16_f32 v252, v12, v13
	v_max_f32_e32 v14, 0, v14
	v_max_f32_e32 v15, 0, v15
	v_mul_f32_e32 v14, v14, v14
	v_mul_f32_e32 v15, v15, v15
	v_cvt_pk_bf16_f32 v253, v14, v15
	s_add_i32 s57, s57, s21
	s_add_i32 s56, s56, s21
	s_cmpk_lt_u32 s57, 0x200
	s_cbranch_scc1 .LBB0_1976
	v_and_b32_e32 v3, 15, v182
	v_lshrrev_b32_e32 v4, 4, v182
	v_mul_u32_u24_e32 v2, 0x2000, v4
	v_lshl_add_u32 v2, v3, 4, v2
	v_mul_u32_u24_e32 v1, 0x110, v4
	v_lshl_add_u32 v1, v3, 4, v1
	v_lshrrev_b32_e32 v3, 7, v182
	v_bfe_u32 v4, v182, 5, 1
	v_lshlrev_b32_e32 v3, 6, v3
	v_lshl_or_b32 v3, v4, 2, v3
	v_mul_u32_u24_e32 v3, 136, v3
	v_and_b32_e32 v4, 0x5f, v182
	v_add_lshl_u32 v0, v3, v4, 1
	s_barrier
	ds_write_b16 v0, v190
	ds_write_b16_d16_hi v0, v190 offset:272
	ds_write_b16 v0, v191 offset:544
	ds_write_b16_d16_hi v0, v191 offset:816
	ds_write_b16 v0, v192 offset:2176
	ds_write_b16_d16_hi v0, v192 offset:2448
	ds_write_b16 v0, v193 offset:2720
	ds_write_b16_d16_hi v0, v193 offset:2992
	ds_write_b16 v0, v194 offset:4352
	ds_write_b16_d16_hi v0, v194 offset:4624
	ds_write_b16 v0, v195 offset:4896
	ds_write_b16_d16_hi v0, v195 offset:5168
	ds_write_b16 v0, v196 offset:6528
	ds_write_b16_d16_hi v0, v196 offset:6800
	ds_write_b16 v0, v197 offset:7072
	ds_write_b16_d16_hi v0, v197 offset:7344
	ds_write_b16 v0, v198 offset:64
	ds_write_b16_d16_hi v0, v198 offset:336
	ds_write_b16 v0, v199 offset:608
	ds_write_b16_d16_hi v0, v199 offset:880
	ds_write_b16 v0, v200 offset:2240
	ds_write_b16_d16_hi v0, v200 offset:2512
	ds_write_b16 v0, v201 offset:2784
	ds_write_b16_d16_hi v0, v201 offset:3056
	ds_write_b16 v0, v202 offset:4416
	ds_write_b16_d16_hi v0, v202 offset:4688
	ds_write_b16 v0, v203 offset:4960
	ds_write_b16_d16_hi v0, v203 offset:5232
	ds_write_b16 v0, v204 offset:6592
	ds_write_b16_d16_hi v0, v204 offset:6864
	ds_write_b16 v0, v205 offset:7136
	ds_write_b16_d16_hi v0, v205 offset:7408
	ds_write_b16 v0, v206 offset:8704
	ds_write_b16_d16_hi v0, v206 offset:8976
	ds_write_b16 v0, v207 offset:9248
	ds_write_b16_d16_hi v0, v207 offset:9520
	ds_write_b16 v0, v208 offset:10880
	ds_write_b16_d16_hi v0, v208 offset:11152
	ds_write_b16 v0, v209 offset:11424
	ds_write_b16_d16_hi v0, v209 offset:11696
	ds_write_b16 v0, v210 offset:13056
	ds_write_b16_d16_hi v0, v210 offset:13328
	ds_write_b16 v0, v211 offset:13600
	ds_write_b16_d16_hi v0, v211 offset:13872
	ds_write_b16 v0, v212 offset:15232
	ds_write_b16_d16_hi v0, v212 offset:15504
	ds_write_b16 v0, v213 offset:15776
	ds_write_b16_d16_hi v0, v213 offset:16048
	ds_write_b16 v0, v214 offset:8768
	ds_write_b16_d16_hi v0, v214 offset:9040
	ds_write_b16 v0, v215 offset:9312
	ds_write_b16_d16_hi v0, v215 offset:9584
	ds_write_b16 v0, v216 offset:10944
	ds_write_b16_d16_hi v0, v216 offset:11216
	ds_write_b16 v0, v217 offset:11488
	ds_write_b16_d16_hi v0, v217 offset:11760
	ds_write_b16 v0, v218 offset:13120
	ds_write_b16_d16_hi v0, v218 offset:13392
	ds_write_b16 v0, v219 offset:13664
	ds_write_b16_d16_hi v0, v219 offset:13936
	ds_write_b16 v0, v220 offset:15296
	ds_write_b16_d16_hi v0, v220 offset:15568
	ds_write_b16 v0, v221 offset:15840
	ds_write_b16_d16_hi v0, v221 offset:16112
	s_waitcnt lgkmcnt(0)
	s_barrier
	ds_read_b128 v[8:11], v1
	ds_read_b128 v[12:15], v1 offset:4352
	ds_read_b128 v[16:19], v1 offset:8704
	ds_read_b128 v[20:23], v1 offset:13056
	ds_read_b128 v[24:27], v1 offset:17408
	ds_read_b128 v[28:31], v1 offset:21760
	ds_read_b128 v[32:35], v1 offset:26112
	ds_read_b128 v[36:39], v1 offset:30464
	s_add_u32 s38, s44, 0x0
	s_addc_u32 s39, s45, 0
	s_waitcnt lgkmcnt(7)
	global_store_dwordx4 v2, v[8:11], s[38:39]
	s_add_u32 s38, s44, 0x20000
	s_addc_u32 s39, s45, 0
	s_waitcnt lgkmcnt(6)
	global_store_dwordx4 v2, v[12:15], s[38:39]
	s_add_u32 s38, s44, 0x40000
	s_addc_u32 s39, s45, 0
	s_waitcnt lgkmcnt(5)
	global_store_dwordx4 v2, v[16:19], s[38:39]
	s_add_u32 s38, s44, 0x60000
	s_addc_u32 s39, s45, 0
	s_waitcnt lgkmcnt(4)
	global_store_dwordx4 v2, v[20:23], s[38:39]
	s_add_u32 s38, s44, 0x100000
	s_addc_u32 s39, s45, 0
	s_waitcnt lgkmcnt(3)
	global_store_dwordx4 v2, v[24:27], s[38:39]
	s_add_u32 s38, s44, 0x120000
	s_addc_u32 s39, s45, 0
	s_waitcnt lgkmcnt(2)
	global_store_dwordx4 v2, v[28:31], s[38:39]
	s_add_u32 s38, s44, 0x140000
	s_addc_u32 s39, s45, 0
	s_waitcnt lgkmcnt(1)
	global_store_dwordx4 v2, v[32:35], s[38:39]
	s_add_u32 s38, s44, 0x160000
	s_addc_u32 s39, s45, 0
	s_waitcnt lgkmcnt(0)
	global_store_dwordx4 v2, v[36:39], s[38:39]
	s_barrier
	ds_write_b16 v0, v222
	ds_write_b16_d16_hi v0, v222 offset:272
	ds_write_b16 v0, v223 offset:544
	ds_write_b16_d16_hi v0, v223 offset:816
	ds_write_b16 v0, v224 offset:2176
	ds_write_b16_d16_hi v0, v224 offset:2448
	ds_write_b16 v0, v225 offset:2720
	ds_write_b16_d16_hi v0, v225 offset:2992
	ds_write_b16 v0, v226 offset:4352
	ds_write_b16_d16_hi v0, v226 offset:4624
	ds_write_b16 v0, v227 offset:4896
	ds_write_b16_d16_hi v0, v227 offset:5168
	ds_write_b16 v0, v228 offset:6528
	ds_write_b16_d16_hi v0, v228 offset:6800
	ds_write_b16 v0, v229 offset:7072
	ds_write_b16_d16_hi v0, v229 offset:7344
	ds_write_b16 v0, v230 offset:64
	ds_write_b16_d16_hi v0, v230 offset:336
	ds_write_b16 v0, v231 offset:608
	ds_write_b16_d16_hi v0, v231 offset:880
	ds_write_b16 v0, v232 offset:2240
	ds_write_b16_d16_hi v0, v232 offset:2512
	ds_write_b16 v0, v233 offset:2784
	ds_write_b16_d16_hi v0, v233 offset:3056
	ds_write_b16 v0, v234 offset:4416
	ds_write_b16_d16_hi v0, v234 offset:4688
	ds_write_b16 v0, v235 offset:4960
	ds_write_b16_d16_hi v0, v235 offset:5232
	ds_write_b16 v0, v236 offset:6592
	ds_write_b16_d16_hi v0, v236 offset:6864
	ds_write_b16 v0, v237 offset:7136
	ds_write_b16_d16_hi v0, v237 offset:7408
	ds_write_b16 v0, v238 offset:8704
	ds_write_b16_d16_hi v0, v238 offset:8976
	ds_write_b16 v0, v239 offset:9248
	ds_write_b16_d16_hi v0, v239 offset:9520
	ds_write_b16 v0, v240 offset:10880
	ds_write_b16_d16_hi v0, v240 offset:11152
	ds_write_b16 v0, v241 offset:11424
	ds_write_b16_d16_hi v0, v241 offset:11696
	ds_write_b16 v0, v242 offset:13056
	ds_write_b16_d16_hi v0, v242 offset:13328
	ds_write_b16 v0, v243 offset:13600
	ds_write_b16_d16_hi v0, v243 offset:13872
	ds_write_b16 v0, v244 offset:15232
	ds_write_b16_d16_hi v0, v244 offset:15504
	ds_write_b16 v0, v245 offset:15776
	ds_write_b16_d16_hi v0, v245 offset:16048
	ds_write_b16 v0, v246 offset:8768
	ds_write_b16_d16_hi v0, v246 offset:9040
	ds_write_b16 v0, v247 offset:9312
	ds_write_b16_d16_hi v0, v247 offset:9584
	ds_write_b16 v0, v248 offset:10944
	ds_write_b16_d16_hi v0, v248 offset:11216
	ds_write_b16 v0, v249 offset:11488
	ds_write_b16_d16_hi v0, v249 offset:11760
	ds_write_b16 v0, v250 offset:13120
	ds_write_b16_d16_hi v0, v250 offset:13392
	ds_write_b16 v0, v251 offset:13664
	ds_write_b16_d16_hi v0, v251 offset:13936
	ds_write_b16 v0, v252 offset:15296
	ds_write_b16_d16_hi v0, v252 offset:15568
	ds_write_b16 v0, v253 offset:15840
	ds_write_b16_d16_hi v0, v253 offset:16112
	s_waitcnt lgkmcnt(0)
	s_barrier
	ds_read_b128 v[8:11], v1
	ds_read_b128 v[12:15], v1 offset:4352
	ds_read_b128 v[16:19], v1 offset:8704
	ds_read_b128 v[20:23], v1 offset:13056
	ds_read_b128 v[24:27], v1 offset:17408
	ds_read_b128 v[28:31], v1 offset:21760
	ds_read_b128 v[32:35], v1 offset:26112
	ds_read_b128 v[36:39], v1 offset:30464
	s_add_u32 s38, s44, 0x80000
	s_addc_u32 s39, s45, 0
	s_waitcnt lgkmcnt(7)
	global_store_dwordx4 v2, v[8:11], s[38:39]
	s_add_u32 s38, s44, 0xa0000
	s_addc_u32 s39, s45, 0
	s_waitcnt lgkmcnt(6)
	global_store_dwordx4 v2, v[12:15], s[38:39]
	s_add_u32 s38, s44, 0xc0000
	s_addc_u32 s39, s45, 0
	s_waitcnt lgkmcnt(5)
	global_store_dwordx4 v2, v[16:19], s[38:39]
	s_add_u32 s38, s44, 0xe0000
	s_addc_u32 s39, s45, 0
	s_waitcnt lgkmcnt(4)
	global_store_dwordx4 v2, v[20:23], s[38:39]
	s_add_u32 s38, s44, 0x180000
	s_addc_u32 s39, s45, 0
	s_waitcnt lgkmcnt(3)
	global_store_dwordx4 v2, v[24:27], s[38:39]
	s_add_u32 s38, s44, 0x1a0000
	s_addc_u32 s39, s45, 0
	s_waitcnt lgkmcnt(2)
	global_store_dwordx4 v2, v[28:31], s[38:39]
	s_add_u32 s38, s44, 0x1c0000
	s_addc_u32 s39, s45, 0
	s_waitcnt lgkmcnt(1)
	global_store_dwordx4 v2, v[32:35], s[38:39]
	s_add_u32 s38, s44, 0x1e0000
	s_addc_u32 s39, s45, 0
	s_waitcnt lgkmcnt(0)
	global_store_dwordx4 v2, v[36:39], s[38:39]
	s_mov_b32 s43, 0
	s_branch .LBB0_1969
